# add nt hint to x_new residual stores in out-proj/down epilogues
# speedup vs baseline: 1.0009x; 1.0009x over previous
;     __device__ __forceinline__ void operator()(const f32x4 (&acc)[2][2][4][2], const Unit& u, int wr, int wc, int fr, int fq) const {
;     ...
;                 if (Hn) {
;                     const float* sp = scn + (size_t)b * 6144 + c0;
;                     gh[bj][0] = *(const f32x4*)(gn + c0) * (*(const f32x4*)sp + 1.f); gh[bj][1] = *(const f32x4*)(gn + c0 + 4) * (*(const f32x4*)(sp + 4) + 1.f);
;                 }
;             }
; #pragma unroll
;             for (int mp = 0; mp < 2; ++mp) {
;                 f32x4 xv[2][2][2];
; #pragma unroll
;                 for (int m2 = 0; m2 < 2; ++m2) {
;                     const int r = rbase + 16 * (2 * mp + m2);
;                     const float* xo = from_input ? ((r < MP) ? xp + (size_t)r * DM : xs + (size_t)(r - MP) * DM) : xbuf + (size_t)r * DM;
; #pragma unroll
;                     for (int bj = 0; bj < 2; ++bj) { xv[m2][bj][0] = *(const f32x4*)(xo + c00 + bj * 128); xv[m2][bj][1] = *(const f32x4*)(xo + c00 + bj * 128 + 4); }
;                 }
; #pragma unroll
;                 for (int m2 = 0; m2 < 2; ++m2) {
;                     const int m = 2 * mp + m2;
;                     const int r = rbase + 16 * m;
;                     float ss = 0.f;
; #pragma unroll
;                     for (int bj = 0; bj < 2; ++bj) {
;                         const int c0 = c00 + bj * 128;
;                         float* xn = xdst + (size_t)r * DM + c0;
;                         const f32x4 y0 = xv[m2][bj][0] + gt[bj][0] * acc[ai][bj][m][0], y1 = xv[m2][bj][1] + gt[bj][1] * acc[ai][bj][m][1];
;                         *(f32x4*)xn = y0; *(f32x4*)(xn + 4) = y1;
;                         if (Hn) {
;                             ss += y0[0] * y0[0] + y0[1] * y0[1] + y0[2] * y0[2] + y0[3] * y0[3] + y1[0] * y1[0] + y1[1] * y1[1] + y1[2] * y1[2] + y1[3] * y1[3];
;                             const f32x4 h0 = y0 * gh[bj][0], h1 = y1 * gh[bj][1];
;                             u32x4 w; w.x = cvtpk(h0[0], h0[1]); w.y = cvtpk(h0[2], h0[3]); w.z = cvtpk(h1[0], h1[1]); w.w = cvtpk(h1[2], h1[3]);
;                             *(u32x4*)(Hn + (size_t)r * DM + c0) = w;
;                         }
;                     }
;                     if (Hn) {
;                         ss += __shfl_xor(ss, 16); ss += __shfl_xor(ss, 32);
;                         if (fq == 0) atomicAdd(rsn + r, ss);
;                     }
.LBB0_1432:
	s_waitcnt vmcnt(0)
	v_pk_add_f32 v[178:179], v[178:179], 1.0 op_sel_hi:[1,0]
	v_pk_add_f32 v[192:193], v[192:193], 1.0 op_sel_hi:[1,0]
	v_pk_mul_f32 v[222:223], v[150:151], v[178:179]
	v_pk_add_f32 v[150:151], v[188:189], 1.0 op_sel_hi:[1,0]
	v_pk_add_f32 v[212:213], v[190:191], 1.0 op_sel_hi:[1,0]
	v_pk_mul_f32 v[190:191], v[184:185], v[192:193]
	v_pk_mul_f32 v[184:185], v[168:169], v[150:151]
	v_pk_add_f32 v[150:151], v[162:163], 1.0 op_sel_hi:[1,0]
	v_pk_mul_f32 v[192:193], v[182:183], v[212:213]
	v_pk_add_f32 v[180:181], v[180:181], 1.0 op_sel_hi:[1,0]
	v_pk_mul_f32 v[182:183], v[146:147], v[150:151]
	v_lshlrev_b64 v[146:147], 12, v[230:231]
	v_pk_mul_f32 v[212:213], v[152:153], v[180:181]
	v_pk_add_f32 v[152:153], v[186:187], 1.0 op_sel_hi:[1,0]
	v_lshl_add_u64 v[146:147], v[228:229], 0, v[146:147]
	v_pk_mul_f32 v[178:179], v[166:167], v[152:153]
	v_pk_add_f32 v[152:153], v[164:165], 1.0 op_sel_hi:[1,0]
	v_lshl_add_u64 v[150:151], v[146:147], 0, v[208:209]
	v_pk_mul_f32 v[180:181], v[148:149], v[152:153]
	global_load_dwordx4 v[162:165], v[150:151], off offset:16
	global_load_dwordx4 v[166:169], v[150:151], off
	global_load_dwordx4 v[146:149], v[150:151], off offset:528
	s_nop 0
	global_load_dwordx4 v[150:153], v[150:151], off offset:512
	v_pk_fma_f32 v[126:127], v[126:127], v[142:143], v[174:175]
	v_pk_fma_f32 v[124:125], v[124:125], v[140:141], v[172:173]
	v_mul_f32_e32 v172, v127, v127
	v_pk_fma_f32 v[128:129], v[128:129], v[144:145], v[176:177]
	v_fmac_f32_e32 v172, v126, v126
	v_fmac_f32_e32 v172, v128, v128
	v_lshlrev_b64 v[186:187], 12, v[224:225]
	v_pk_fma_f32 v[122:123], v[122:123], v[138:139], v[170:171]
	v_fmac_f32_e32 v172, v129, v129
	v_lshl_add_u64 v[186:187], s[92:93], 0, v[186:187]
	v_fmac_f32_e32 v172, v122, v122
	v_lshl_add_u64 v[186:187], v[186:187], 0, v[208:209]
	v_fmac_f32_e32 v172, v123, v123
	global_store_dwordx4 v[186:187], v[126:129], off nt
	global_store_dwordx4 v[186:187], v[122:125], off offset:16 nt
	v_fmac_f32_e32 v172, v124, v124
	v_pk_mul_f32 v[126:127], v[192:193], v[126:127]
	v_fmac_f32_e32 v172, v125, v125
	v_pk_mul_f32 v[170:171], v[212:213], v[124:125]
	v_pk_mul_f32 v[124:125], v[222:223], v[122:123]
	v_cvt_pk_bf16_f32 v122, v126, v127
	v_lshlrev_b64 v[126:127], 11, v[224:225]
	v_pk_mul_f32 v[128:129], v[190:191], v[128:129]
	v_lshl_add_u64 v[126:127], s[80:81], 0, v[126:127]
	v_cvt_pk_bf16_f32 v123, v128, v129
	v_cvt_pk_bf16_f32 v124, v124, v125
	v_cvt_pk_bf16_f32 v125, v170, v171
	v_lshl_add_u64 v[126:127], v[206:207], 1, v[126:127]
	v_pk_fma_f32 v[120:121], v[120:121], v[136:137], v[160:161]
	v_pk_fma_f32 v[118:119], v[118:119], v[134:135], v[158:159]
	global_store_dwordx4 v[126:127], v[122:125], off
	v_pk_fma_f32 v[114:115], v[114:115], v[130:131], v[154:155]
	v_pk_fma_f32 v[116:117], v[116:117], v[132:133], v[156:157]
	global_store_dwordx4 v[186:187], v[118:121], off offset:512 nt
	global_store_dwordx4 v[186:187], v[114:117], off offset:528 nt
	v_pk_mul_f32 v[122:123], v[178:179], v[118:119]
	v_mul_f32_e32 v119, v119, v119
	v_fmac_f32_e32 v119, v118, v118
	v_fmac_f32_e32 v119, v120, v120
	v_fmac_f32_e32 v119, v121, v121
	v_fmac_f32_e32 v119, v114, v114
	v_fmac_f32_e32 v119, v115, v115
	v_pk_mul_f32 v[128:129], v[180:181], v[116:117]
	v_fmac_f32_e32 v119, v116, v116
	v_and_b32_e32 v116, 64, v248
	v_pk_mul_f32 v[154:155], v[182:183], v[114:115]
	v_xor_b32_e32 v115, 16, v248
	v_add_u32_e32 v116, 64, v116
	v_cmp_lt_i32_e32 vcc, v115, v116
	v_fmac_f32_e32 v119, v117, v117
	v_add_f32_e32 v114, v172, v119
	v_cndmask_b32_e32 v115, v248, v115, vcc
	v_lshlrev_b32_e32 v156, 2, v115
	ds_bpermute_b32 v115, v156, v114
	v_pk_mul_f32 v[124:125], v[184:185], v[120:121]
	v_cvt_pk_bf16_f32 v122, v122, v123
	v_cvt_pk_bf16_f32 v123, v124, v125
	v_cvt_pk_bf16_f32 v124, v154, v155
	s_waitcnt lgkmcnt(0)
	v_add_f32_e32 v114, v114, v115
	v_xor_b32_e32 v115, 32, v248
	v_cmp_lt_i32_e32 vcc, v115, v116
	v_cvt_pk_bf16_f32 v125, v128, v129
	v_lshl_add_u64 v[154:155], v[224:225], 2, s[52:53]
	v_cndmask_b32_e32 v115, v248, v115, vcc
	v_lshlrev_b32_e32 v157, 2, v115
	ds_bpermute_b32 v115, v157, v114
	global_store_dwordx4 v[126:127], v[122:125], off offset:256
	s_and_saveexec_b64 s[2:3], s[38:39]
	s_cbranch_execz .LBB0_1434
	s_waitcnt lgkmcnt(0)
	v_add_f32_e32 v114, v114, v115
	global_atomic_add_f32 v[154:155], v114, off
; __device__ __forceinline__ unsigned cvtpk(float lo, float hi) { f32x2_t v = {lo, hi}; bf16x2_t b = __builtin_convertvector(v, bf16x2_t); return __builtin_bit_cast(unsigned, b); }
;     __device__ __forceinline__ void operator()(const f32x4 (&acc)[2][2][4][2], const Unit& u, int wr, int wc, int fr, int fq) const {
;     ...
;                 for (int m2 = 0; m2 < 2; ++m2) {
;                     const int m = 2 * mp + m2;
;                     const int r = rbase + 16 * m;
;                     float ss = 0.f;
; #pragma unroll
;                     for (int bj = 0; bj < 2; ++bj) {
;                         const int c0 = c00 + bj * 128;
;                         float* xn = xdst + (size_t)r * DM + c0;
;                         const f32x4 y0 = xv[m2][bj][0] + gt[bj][0] * acc[ai][bj][m][0], y1 = xv[m2][bj][1] + gt[bj][1] * acc[ai][bj][m][1];
;                         *(f32x4*)xn = y0; *(f32x4*)(xn + 4) = y1;
;                         if (Hn) {
;                             ss += y0[0] * y0[0] + y0[1] * y0[1] + y0[2] * y0[2] + y0[3] * y0[3] + y1[0] * y1[0] + y1[1] * y1[1] + y1[2] * y1[2] + y1[3] * y1[3];
;                             const f32x4 h0 = y0 * gh[bj][0], h1 = y1 * gh[bj][1];
;                             u32x4 w; w.x = cvtpk(h0[0], h0[1]); w.y = cvtpk(h0[2], h0[3]); w.z = cvtpk(h1[0], h1[1]); w.w = cvtpk(h1[2], h1[3]);
;                             *(u32x4*)(Hn + (size_t)r * DM + c0) = w;
;                         }
;                     }
;                     if (Hn) {
;                         ss += __shfl_xor(ss, 16); ss += __shfl_xor(ss, 32);
;                         if (fq == 0) atomicAdd(rsn + r, ss);
;                     }
.LBB0_1434:
	s_or_b64 exec, exec, s[2:3]
	s_waitcnt vmcnt(8)
	v_pk_fma_f32 v[110:111], v[110:111], v[142:143], v[166:167]
	v_pk_fma_f32 v[112:113], v[112:113], v[144:145], v[168:169]
	v_mul_f32_e32 v118, v111, v111
	v_fmac_f32_e32 v118, v110, v110
	v_fmac_f32_e32 v118, v112, v112
	s_waitcnt lgkmcnt(0)
	v_lshlrev_b64 v[114:115], 12, v[226:227]
	v_pk_fma_f32 v[106:107], v[106:107], v[138:139], v[162:163]
	v_fmac_f32_e32 v118, v113, v113
	v_lshl_add_u64 v[114:115], s[92:93], 0, v[114:115]
	v_fmac_f32_e32 v118, v106, v106
	v_lshl_add_u64 v[114:115], v[206:207], 2, v[114:115]
	v_pk_fma_f32 v[108:109], v[108:109], v[140:141], v[164:165]
	v_fmac_f32_e32 v118, v107, v107
	global_store_dwordx4 v[114:115], v[110:113], off nt
	global_store_dwordx4 v[114:115], v[106:109], off offset:16 nt
	v_fmac_f32_e32 v118, v108, v108
	v_pk_mul_f32 v[110:111], v[192:193], v[110:111]
	v_fmac_f32_e32 v118, v109, v109
	v_pk_mul_f32 v[116:117], v[212:213], v[108:109]
	v_pk_mul_f32 v[108:109], v[222:223], v[106:107]
	v_cvt_pk_bf16_f32 v106, v110, v111
	v_lshlrev_b64 v[110:111], 11, v[226:227]
	v_pk_mul_f32 v[112:113], v[190:191], v[112:113]
	v_lshl_add_u64 v[110:111], s[80:81], 0, v[110:111]
	v_cvt_pk_bf16_f32 v107, v112, v113
	v_cvt_pk_bf16_f32 v108, v108, v109
	v_cvt_pk_bf16_f32 v109, v116, v117
	v_lshl_add_u64 v[110:111], v[206:207], 1, v[110:111]
	s_waitcnt vmcnt(8)
	v_pk_fma_f32 v[102:103], v[102:103], v[134:135], v[150:151]
	global_store_dwordx4 v[110:111], v[106:109], off
	v_pk_fma_f32 v[104:105], v[104:105], v[136:137], v[152:153]
	v_pk_fma_f32 v[98:99], v[98:99], v[130:131], v[146:147]
	v_mul_f32_e32 v108, v103, v103
	v_fmac_f32_e32 v108, v102, v102
	v_fmac_f32_e32 v108, v104, v104
	v_fmac_f32_e32 v108, v105, v105
	v_fmac_f32_e32 v108, v98, v98
	v_pk_fma_f32 v[100:101], v[100:101], v[132:133], v[148:149]
	v_fmac_f32_e32 v108, v99, v99
	v_fmac_f32_e32 v108, v100, v100
	v_fmac_f32_e32 v108, v101, v101
	v_add_f32_e32 v112, v118, v108
	ds_bpermute_b32 v113, v156, v112
	global_store_dwordx4 v[114:115], v[102:105], off offset:512 nt
	global_store_dwordx4 v[114:115], v[98:101], off offset:528 nt
	v_pk_mul_f32 v[108:109], v[182:183], v[98:99]
	v_pk_mul_f32 v[106:107], v[184:185], v[104:105]
	v_pk_mul_f32 v[102:103], v[178:179], v[102:103]
	s_waitcnt lgkmcnt(0)
	v_add_f32_e32 v98, v112, v113
	ds_bpermute_b32 v99, v157, v98
	v_pk_mul_f32 v[104:105], v[180:181], v[100:101]
	v_cvt_pk_bf16_f32 v100, v102, v103
	v_cvt_pk_bf16_f32 v101, v106, v107
	v_cvt_pk_bf16_f32 v102, v108, v109
	v_cvt_pk_bf16_f32 v103, v104, v105
	global_store_dwordx4 v[110:111], v[100:103], off offset:256
	s_and_saveexec_b64 s[2:3], s[38:39]
	s_cbranch_execz .LBB0_1436
	s_waitcnt lgkmcnt(0)
	v_add_f32_e32 v98, v98, v99
	global_atomic_add_f32 v[154:155], v98, off offset:64

; __device__ __forceinline__ unsigned cvtpk(float lo, float hi) { f32x2_t v = {lo, hi}; bf16x2_t b = __builtin_convertvector(v, bf16x2_t); return __builtin_bit_cast(unsigned, b); }
;     __device__ __forceinline__ void operator()(const f32x4 (&acc)[2][2][4][2], const Unit& u, int wr, int wc, int fr, int fq) const {
;     ...
;                 f32x4 xv[2][2][2];
; #pragma unroll
;                 for (int m2 = 0; m2 < 2; ++m2) {
;                     const int r = rbase + 16 * (2 * mp + m2);
;                     const float* xo = from_input ? ((r < MP) ? xp + (size_t)r * DM : xs + (size_t)(r - MP) * DM) : xbuf + (size_t)r * DM;
; #pragma unroll
;                     for (int bj = 0; bj < 2; ++bj) { xv[m2][bj][0] = *(const f32x4*)(xo + c00 + bj * 128); xv[m2][bj][1] = *(const f32x4*)(xo + c00 + bj * 128 + 4); }
;                 }
; #pragma unroll
;                 for (int m2 = 0; m2 < 2; ++m2) {
;                     const int m = 2 * mp + m2;
;                     const int r = rbase + 16 * m;
;                     float ss = 0.f;
; #pragma unroll
;                     for (int bj = 0; bj < 2; ++bj) {
;                         const int c0 = c00 + bj * 128;
;                         float* xn = xdst + (size_t)r * DM + c0;
;                         const f32x4 y0 = xv[m2][bj][0] + gt[bj][0] * acc[ai][bj][m][0], y1 = xv[m2][bj][1] + gt[bj][1] * acc[ai][bj][m][1];
;                         *(f32x4*)xn = y0; *(f32x4*)(xn + 4) = y1;
;                         if (Hn) {
;                             ss += y0[0] * y0[0] + y0[1] * y0[1] + y0[2] * y0[2] + y0[3] * y0[3] + y1[0] * y1[0] + y1[1] * y1[1] + y1[2] * y1[2] + y1[3] * y1[3];
;                             const f32x4 h0 = y0 * gh[bj][0], h1 = y1 * gh[bj][1];
;                             u32x4 w; w.x = cvtpk(h0[0], h0[1]); w.y = cvtpk(h0[2], h0[3]); w.z = cvtpk(h1[0], h1[1]); w.w = cvtpk(h1[2], h1[3]);
;                             *(u32x4*)(Hn + (size_t)r * DM + c0) = w;
;                         }
;                     }
;                     if (Hn) {
;                         ss += __shfl_xor(ss, 16); ss += __shfl_xor(ss, 32);
;                         if (fq == 0) atomicAdd(rsn + r, ss);
;                     }
.LBB0_1452:
	v_lshlrev_b64 v[100:101], 12, v[100:101]
	v_lshl_add_u64 v[98:99], v[98:99], 0, v[100:101]
	v_lshl_add_u64 v[102:103], v[98:99], 0, v[208:209]
	global_load_dwordx4 v[106:109], v[102:103], off offset:16
	global_load_dwordx4 v[114:117], v[102:103], off
	global_load_dwordx4 v[98:101], v[102:103], off offset:528
	s_nop 0
	global_load_dwordx4 v[102:105], v[102:103], off offset:512
	s_waitcnt vmcnt(6)
	v_pk_fma_f32 v[94:95], v[94:95], v[142:143], v[126:127]
	v_pk_fma_f32 v[92:93], v[92:93], v[140:141], v[124:125]
	v_mul_f32_e32 v124, v95, v95
	v_pk_fma_f32 v[96:97], v[96:97], v[144:145], v[128:129]
	v_fmac_f32_e32 v124, v94, v94
	v_fmac_f32_e32 v124, v96, v96
	v_lshlrev_b64 v[150:151], 12, v[148:149]
	v_pk_fma_f32 v[90:91], v[90:91], v[138:139], v[122:123]
	v_fmac_f32_e32 v124, v97, v97
	v_lshl_add_u64 v[150:151], s[92:93], 0, v[150:151]
	v_fmac_f32_e32 v124, v90, v90
	v_lshl_add_u64 v[150:151], v[150:151], 0, v[208:209]
	v_fmac_f32_e32 v124, v91, v91
	global_store_dwordx4 v[150:151], v[94:97], off nt
	global_store_dwordx4 v[150:151], v[90:93], off offset:16 nt
	v_fmac_f32_e32 v124, v92, v92
	v_pk_mul_f32 v[94:95], v[192:193], v[94:95]
	v_fmac_f32_e32 v124, v93, v93
	v_pk_mul_f32 v[122:123], v[212:213], v[92:93]
	v_pk_mul_f32 v[92:93], v[222:223], v[90:91]
	v_cvt_pk_bf16_f32 v90, v94, v95
	v_lshlrev_b64 v[94:95], 11, v[148:149]
	v_pk_mul_f32 v[96:97], v[190:191], v[96:97]
	v_lshl_add_u64 v[94:95], s[80:81], 0, v[94:95]
	v_cvt_pk_bf16_f32 v91, v96, v97
	v_cvt_pk_bf16_f32 v92, v92, v93
	v_cvt_pk_bf16_f32 v93, v122, v123
	v_lshl_add_u64 v[94:95], v[206:207], 1, v[94:95]
	s_waitcnt vmcnt(6)
	v_pk_fma_f32 v[86:87], v[86:87], v[134:135], v[118:119]
	global_store_dwordx4 v[94:95], v[90:93], off
	v_pk_fma_f32 v[88:89], v[88:89], v[136:137], v[120:121]
	v_pk_fma_f32 v[82:83], v[82:83], v[130:131], v[110:111]
	v_mul_f32_e32 v92, v87, v87
	v_fmac_f32_e32 v92, v86, v86
	v_fmac_f32_e32 v92, v88, v88
	v_fmac_f32_e32 v92, v89, v89
	v_fmac_f32_e32 v92, v82, v82
	v_pk_fma_f32 v[84:85], v[84:85], v[132:133], v[112:113]
	v_fmac_f32_e32 v92, v83, v83
	v_fmac_f32_e32 v92, v84, v84
	v_fmac_f32_e32 v92, v85, v85
	v_add_f32_e32 v96, v124, v92
	ds_bpermute_b32 v97, v156, v96
	global_store_dwordx4 v[150:151], v[86:89], off offset:512 nt
	global_store_dwordx4 v[150:151], v[82:85], off offset:528 nt
	v_pk_mul_f32 v[92:93], v[182:183], v[82:83]
	v_pk_mul_f32 v[90:91], v[184:185], v[88:89]
	v_pk_mul_f32 v[86:87], v[178:179], v[86:87]
	s_waitcnt lgkmcnt(0)
	v_add_f32_e32 v82, v96, v97
	ds_bpermute_b32 v83, v157, v82
	v_pk_mul_f32 v[88:89], v[180:181], v[84:85]
	v_cvt_pk_bf16_f32 v84, v86, v87
	v_cvt_pk_bf16_f32 v85, v90, v91
	v_cvt_pk_bf16_f32 v86, v92, v93
	v_cvt_pk_bf16_f32 v87, v88, v89
	global_store_dwordx4 v[94:95], v[84:87], off offset:256
	s_and_saveexec_b64 s[2:3], s[38:39]
	s_cbranch_execz .LBB0_1454
	s_waitcnt lgkmcnt(0)
	v_add_f32_e32 v82, v82, v83
	global_atomic_add_f32 v[154:155], v82, off offset:128
.LBB0_1454:
	s_or_b64 exec, exec, s[2:3]
	s_waitcnt vmcnt(8)
	v_pk_fma_f32 v[78:79], v[78:79], v[142:143], v[114:115]
	v_pk_fma_f32 v[80:81], v[80:81], v[144:145], v[116:117]
	v_mul_f32_e32 v86, v79, v79
	v_fmac_f32_e32 v86, v78, v78
	v_fmac_f32_e32 v86, v80, v80
	s_waitcnt lgkmcnt(0)
	v_lshlrev_b64 v[82:83], 12, v[146:147]
	v_pk_fma_f32 v[74:75], v[74:75], v[138:139], v[106:107]
	v_fmac_f32_e32 v86, v81, v81
	v_lshl_add_u64 v[82:83], s[92:93], 0, v[82:83]
	v_fmac_f32_e32 v86, v74, v74
	v_lshl_add_u64 v[82:83], v[206:207], 2, v[82:83]
	v_pk_fma_f32 v[76:77], v[76:77], v[140:141], v[108:109]
	v_fmac_f32_e32 v86, v75, v75
	global_store_dwordx4 v[82:83], v[78:81], off nt
	global_store_dwordx4 v[82:83], v[74:77], off offset:16 nt
	v_fmac_f32_e32 v86, v76, v76
	v_pk_mul_f32 v[78:79], v[192:193], v[78:79]
	v_fmac_f32_e32 v86, v77, v77
	v_pk_mul_f32 v[84:85], v[212:213], v[76:77]
	v_pk_mul_f32 v[76:77], v[222:223], v[74:75]
	v_cvt_pk_bf16_f32 v74, v78, v79
	v_lshlrev_b64 v[78:79], 11, v[146:147]
	v_pk_mul_f32 v[80:81], v[190:191], v[80:81]
	v_lshl_add_u64 v[78:79], s[80:81], 0, v[78:79]
	v_cvt_pk_bf16_f32 v75, v80, v81
	v_cvt_pk_bf16_f32 v76, v76, v77
	v_cvt_pk_bf16_f32 v77, v84, v85
	v_lshl_add_u64 v[78:79], v[206:207], 1, v[78:79]
	s_waitcnt vmcnt(8)
	v_pk_fma_f32 v[70:71], v[70:71], v[134:135], v[102:103]
	global_store_dwordx4 v[78:79], v[74:77], off
	v_pk_fma_f32 v[72:73], v[72:73], v[136:137], v[104:105]
	v_pk_fma_f32 v[66:67], v[66:67], v[130:131], v[98:99]
	v_mul_f32_e32 v76, v71, v71
	v_fmac_f32_e32 v76, v70, v70
	v_fmac_f32_e32 v76, v72, v72
	v_fmac_f32_e32 v76, v73, v73
	v_fmac_f32_e32 v76, v66, v66
	v_pk_fma_f32 v[68:69], v[68:69], v[132:133], v[100:101]
	v_fmac_f32_e32 v76, v67, v67
	v_fmac_f32_e32 v76, v68, v68
	v_fmac_f32_e32 v76, v69, v69
	v_add_f32_e32 v80, v86, v76
	ds_bpermute_b32 v81, v156, v80
	global_store_dwordx4 v[82:83], v[70:73], off offset:512 nt
	global_store_dwordx4 v[82:83], v[66:69], off offset:528 nt
	v_pk_mul_f32 v[76:77], v[182:183], v[66:67]
	v_pk_mul_f32 v[74:75], v[184:185], v[72:73]
	v_pk_mul_f32 v[70:71], v[178:179], v[70:71]
	s_waitcnt lgkmcnt(0)
	v_add_f32_e32 v66, v80, v81
	ds_bpermute_b32 v67, v157, v66
	v_pk_mul_f32 v[72:73], v[180:181], v[68:69]
	v_cvt_pk_bf16_f32 v68, v70, v71
	v_cvt_pk_bf16_f32 v69, v74, v75
	v_cvt_pk_bf16_f32 v70, v76, v77
	v_cvt_pk_bf16_f32 v71, v72, v73
	global_store_dwordx4 v[78:79], v[68:71], off offset:256
	s_and_saveexec_b64 s[2:3], s[38:39]
	s_cbranch_execz .LBB0_1456
	s_waitcnt lgkmcnt(0)
	v_add_f32_e32 v66, v66, v67
	global_atomic_add_f32 v[154:155], v66, off offset:192

;     __device__ __forceinline__ void operator()(const f32x4 (&acc)[2][2][4][2], const Unit& u, int wr, int wc, int fr, int fq) const {
;     ...
;                 if (Hn) {
;                     const float* sp = scn + (size_t)b * 6144 + c0;
;                     gh[bj][0] = *(const f32x4*)(gn + c0) * (*(const f32x4*)sp + 1.f); gh[bj][1] = *(const f32x4*)(gn + c0 + 4) * (*(const f32x4*)(sp + 4) + 1.f);
;                 }
;             }
; #pragma unroll
;             for (int mp = 0; mp < 2; ++mp) {
;                 f32x4 xv[2][2][2];
; #pragma unroll
;                 for (int m2 = 0; m2 < 2; ++m2) {
;                     const int r = rbase + 16 * (2 * mp + m2);
;                     const float* xo = from_input ? ((r < MP) ? xp + (size_t)r * DM : xs + (size_t)(r - MP) * DM) : xbuf + (size_t)r * DM;
; #pragma unroll
;                     for (int bj = 0; bj < 2; ++bj) { xv[m2][bj][0] = *(const f32x4*)(xo + c00 + bj * 128); xv[m2][bj][1] = *(const f32x4*)(xo + c00 + bj * 128 + 4); }
;                 }
; #pragma unroll
;                 for (int m2 = 0; m2 < 2; ++m2) {
;                     const int m = 2 * mp + m2;
;                     const int r = rbase + 16 * m;
;                     float ss = 0.f;
; #pragma unroll
;                     for (int bj = 0; bj < 2; ++bj) {
;                         const int c0 = c00 + bj * 128;
;                         float* xn = xdst + (size_t)r * DM + c0;
;                         const f32x4 y0 = xv[m2][bj][0] + gt[bj][0] * acc[ai][bj][m][0], y1 = xv[m2][bj][1] + gt[bj][1] * acc[ai][bj][m][1];
;                         *(f32x4*)xn = y0; *(f32x4*)(xn + 4) = y1;
;                         if (Hn) {
;                             ss += y0[0] * y0[0] + y0[1] * y0[1] + y0[2] * y0[2] + y0[3] * y0[3] + y1[0] * y1[0] + y1[1] * y1[1] + y1[2] * y1[2] + y1[3] * y1[3];
;                             const f32x4 h0 = y0 * gh[bj][0], h1 = y1 * gh[bj][1];
;                             u32x4 w; w.x = cvtpk(h0[0], h0[1]); w.y = cvtpk(h0[2], h0[3]); w.z = cvtpk(h1[0], h1[1]); w.w = cvtpk(h1[2], h1[3]);
;                             *(u32x4*)(Hn + (size_t)r * DM + c0) = w;
;                         }
;                     }
;                     if (Hn) {
;                         ss += __shfl_xor(ss, 16); ss += __shfl_xor(ss, 32);
;                         if (fq == 0) atomicAdd(rsn + r, ss);
;                     }
.LBB0_1472:
	s_waitcnt vmcnt(11)
	v_pk_add_f32 v[114:115], v[114:115], 1.0 op_sel_hi:[1,0]
	s_waitcnt vmcnt(10)
	v_pk_add_f32 v[128:129], v[128:129], 1.0 op_sel_hi:[1,0]
	v_pk_mul_f32 v[132:133], v[90:91], v[114:115]
	s_waitcnt vmcnt(4)
	v_pk_add_f32 v[90:91], v[124:125], 1.0 op_sel_hi:[1,0]
	v_pk_add_f32 v[130:131], v[126:127], 1.0 op_sel_hi:[1,0]
	v_pk_mul_f32 v[126:127], v[120:121], v[128:129]
	v_pk_mul_f32 v[120:121], v[108:109], v[90:91]
	v_pk_add_f32 v[90:91], v[98:99], 1.0 op_sel_hi:[1,0]
	v_pk_mul_f32 v[128:129], v[118:119], v[130:131]
	v_pk_add_f32 v[116:117], v[116:117], 1.0 op_sel_hi:[1,0]
	v_pk_mul_f32 v[118:119], v[82:83], v[90:91]
	v_lshlrev_b64 v[82:83], 12, v[140:141]
	v_pk_mul_f32 v[130:131], v[92:93], v[116:117]
	v_pk_add_f32 v[92:93], v[122:123], 1.0 op_sel_hi:[1,0]
	v_lshl_add_u64 v[82:83], v[138:139], 0, v[82:83]
	v_pk_mul_f32 v[114:115], v[106:107], v[92:93]
	v_pk_add_f32 v[92:93], v[100:101], 1.0 op_sel_hi:[1,0]
	v_lshl_add_u64 v[90:91], v[82:83], 0, v[208:209]
	v_pk_mul_f32 v[116:117], v[84:85], v[92:93]
	global_load_dwordx4 v[98:101], v[90:91], off offset:16
	global_load_dwordx4 v[106:109], v[90:91], off
	global_load_dwordx4 v[82:85], v[90:91], off offset:528
	s_nop 0
	global_load_dwordx4 v[90:93], v[90:91], off offset:512
	s_waitcnt vmcnt(6)
	v_pk_fma_f32 v[62:63], v[62:63], v[78:79], v[110:111]
	v_pk_fma_f32 v[60:61], v[60:61], v[76:77], v[104:105]
	v_mul_f32_e32 v104, v63, v63
	v_pk_fma_f32 v[64:65], v[64:65], v[80:81], v[112:113]
	v_fmac_f32_e32 v104, v62, v62
	v_fmac_f32_e32 v104, v64, v64
	v_lshlrev_b64 v[122:123], 12, v[134:135]
	v_pk_fma_f32 v[58:59], v[58:59], v[74:75], v[102:103]
	v_fmac_f32_e32 v104, v65, v65
	v_lshl_add_u64 v[122:123], s[92:93], 0, v[122:123]
	v_fmac_f32_e32 v104, v58, v58
	v_lshl_add_u64 v[122:123], v[122:123], 0, v[208:209]
	v_fmac_f32_e32 v104, v59, v59
	global_store_dwordx4 v[122:123], v[62:65], off nt
	global_store_dwordx4 v[122:123], v[58:61], off offset:16 nt
	v_fmac_f32_e32 v104, v60, v60
	v_pk_mul_f32 v[62:63], v[128:129], v[62:63]
	v_fmac_f32_e32 v104, v61, v61
	v_pk_mul_f32 v[102:103], v[130:131], v[60:61]
	v_pk_mul_f32 v[60:61], v[132:133], v[58:59]
	v_cvt_pk_bf16_f32 v58, v62, v63
	v_lshlrev_b64 v[62:63], 11, v[134:135]
	v_pk_mul_f32 v[64:65], v[126:127], v[64:65]
	v_lshl_add_u64 v[62:63], s[80:81], 0, v[62:63]
	v_cvt_pk_bf16_f32 v59, v64, v65
	v_cvt_pk_bf16_f32 v60, v60, v61
	v_cvt_pk_bf16_f32 v61, v102, v103
	v_lshl_add_u64 v[62:63], v[206:207], 1, v[62:63]
	s_waitcnt vmcnt(6)
	v_pk_fma_f32 v[56:57], v[56:57], v[72:73], v[96:97]
	v_pk_fma_f32 v[54:55], v[54:55], v[70:71], v[94:95]
	global_store_dwordx4 v[62:63], v[58:61], off
	v_pk_fma_f32 v[50:51], v[50:51], v[66:67], v[86:87]
	v_pk_fma_f32 v[52:53], v[52:53], v[68:69], v[88:89]
	global_store_dwordx4 v[122:123], v[54:57], off offset:512 nt
	global_store_dwordx4 v[122:123], v[50:53], off offset:528 nt
	v_pk_mul_f32 v[58:59], v[114:115], v[54:55]
	v_mul_f32_e32 v55, v55, v55
	v_fmac_f32_e32 v55, v54, v54
	v_fmac_f32_e32 v55, v56, v56
	v_fmac_f32_e32 v55, v57, v57
	v_fmac_f32_e32 v55, v50, v50
	v_fmac_f32_e32 v55, v51, v51
	v_fmac_f32_e32 v55, v52, v52
	v_fmac_f32_e32 v55, v53, v53
	v_pk_mul_f32 v[86:87], v[118:119], v[50:51]
	v_add_f32_e32 v50, v104, v55
	ds_bpermute_b32 v51, v156, v50
	v_pk_mul_f32 v[60:61], v[120:121], v[56:57]
	v_pk_mul_f32 v[64:65], v[116:117], v[52:53]
	v_cvt_pk_bf16_f32 v58, v58, v59
	v_cvt_pk_bf16_f32 v59, v60, v61
	s_waitcnt lgkmcnt(0)
	v_add_f32_e32 v50, v50, v51
	ds_bpermute_b32 v51, v157, v50
	v_cvt_pk_bf16_f32 v60, v86, v87
	v_cvt_pk_bf16_f32 v61, v64, v65
	v_lshl_add_u64 v[86:87], v[134:135], 2, s[52:53]
	global_store_dwordx4 v[62:63], v[58:61], off offset:256
	s_and_saveexec_b64 s[2:3], s[38:39]
	s_cbranch_execz .LBB0_1474
	s_waitcnt lgkmcnt(0)
	v_add_f32_e32 v50, v50, v51
	global_atomic_add_f32 v[86:87], v50, off
.LBB0_1474:
	s_or_b64 exec, exec, s[2:3]
	s_waitcnt vmcnt(8)
	v_pk_fma_f32 v[46:47], v[46:47], v[78:79], v[106:107]
	v_pk_fma_f32 v[48:49], v[48:49], v[80:81], v[108:109]
	v_mul_f32_e32 v54, v47, v47
	v_fmac_f32_e32 v54, v46, v46
	v_fmac_f32_e32 v54, v48, v48
	s_waitcnt lgkmcnt(0)
	v_lshlrev_b64 v[50:51], 12, v[136:137]
	v_pk_fma_f32 v[42:43], v[42:43], v[74:75], v[98:99]
	v_fmac_f32_e32 v54, v49, v49
	v_lshl_add_u64 v[50:51], s[92:93], 0, v[50:51]
	v_fmac_f32_e32 v54, v42, v42
	v_lshl_add_u64 v[50:51], v[206:207], 2, v[50:51]
	v_pk_fma_f32 v[44:45], v[44:45], v[76:77], v[100:101]
	v_fmac_f32_e32 v54, v43, v43
	global_store_dwordx4 v[50:51], v[46:49], off nt
	global_store_dwordx4 v[50:51], v[42:45], off offset:16 nt
	v_fmac_f32_e32 v54, v44, v44
	v_pk_mul_f32 v[46:47], v[128:129], v[46:47]
	v_fmac_f32_e32 v54, v45, v45
	v_pk_mul_f32 v[52:53], v[130:131], v[44:45]
	v_pk_mul_f32 v[44:45], v[132:133], v[42:43]
	v_cvt_pk_bf16_f32 v42, v46, v47
	v_lshlrev_b64 v[46:47], 11, v[136:137]
	v_pk_mul_f32 v[48:49], v[126:127], v[48:49]
	v_lshl_add_u64 v[46:47], s[80:81], 0, v[46:47]
	v_cvt_pk_bf16_f32 v43, v48, v49
	v_cvt_pk_bf16_f32 v44, v44, v45
	v_cvt_pk_bf16_f32 v45, v52, v53
	v_lshl_add_u64 v[46:47], v[206:207], 1, v[46:47]
	s_waitcnt vmcnt(8)
	v_pk_fma_f32 v[38:39], v[38:39], v[70:71], v[90:91]
	global_store_dwordx4 v[46:47], v[42:45], off
	v_pk_fma_f32 v[40:41], v[40:41], v[72:73], v[92:93]
	v_pk_fma_f32 v[34:35], v[34:35], v[66:67], v[82:83]
	v_mul_f32_e32 v44, v39, v39
	v_fmac_f32_e32 v44, v38, v38
	v_fmac_f32_e32 v44, v40, v40
	v_fmac_f32_e32 v44, v41, v41
	v_fmac_f32_e32 v44, v34, v34
	v_pk_fma_f32 v[36:37], v[36:37], v[68:69], v[84:85]
	v_fmac_f32_e32 v44, v35, v35
	v_fmac_f32_e32 v44, v36, v36
	v_fmac_f32_e32 v44, v37, v37
	v_add_f32_e32 v48, v54, v44
	ds_bpermute_b32 v49, v156, v48
	global_store_dwordx4 v[50:51], v[38:41], off offset:512 nt
	global_store_dwordx4 v[50:51], v[34:37], off offset:528 nt
	v_pk_mul_f32 v[44:45], v[118:119], v[34:35]
	v_pk_mul_f32 v[42:43], v[120:121], v[40:41]
	v_pk_mul_f32 v[38:39], v[114:115], v[38:39]
	s_waitcnt lgkmcnt(0)
	v_add_f32_e32 v34, v48, v49
	ds_bpermute_b32 v35, v157, v34
	v_pk_mul_f32 v[40:41], v[116:117], v[36:37]
	v_cvt_pk_bf16_f32 v36, v38, v39
	v_cvt_pk_bf16_f32 v37, v42, v43
	v_cvt_pk_bf16_f32 v38, v44, v45
	v_cvt_pk_bf16_f32 v39, v40, v41
	global_store_dwordx4 v[46:47], v[36:39], off offset:256
	s_and_saveexec_b64 s[2:3], s[38:39]
	s_cbranch_execz .LBB0_1476
	s_waitcnt lgkmcnt(0)
	v_add_f32_e32 v34, v34, v35
	global_atomic_add_f32 v[86:87], v34, off offset:64

; __device__ __forceinline__ unsigned cvtpk(float lo, float hi) { f32x2_t v = {lo, hi}; bf16x2_t b = __builtin_convertvector(v, bf16x2_t); return __builtin_bit_cast(unsigned, b); }
;     __device__ __forceinline__ void operator()(const f32x4 (&acc)[2][2][4][2], const Unit& u, int wr, int wc, int fr, int fq) const {
;     ...
;                 f32x4 xv[2][2][2];
; #pragma unroll
;                 for (int m2 = 0; m2 < 2; ++m2) {
;                     const int r = rbase + 16 * (2 * mp + m2);
;                     const float* xo = from_input ? ((r < MP) ? xp + (size_t)r * DM : xs + (size_t)(r - MP) * DM) : xbuf + (size_t)r * DM;
; #pragma unroll
;                     for (int bj = 0; bj < 2; ++bj) { xv[m2][bj][0] = *(const f32x4*)(xo + c00 + bj * 128); xv[m2][bj][1] = *(const f32x4*)(xo + c00 + bj * 128 + 4); }
;                 }
; #pragma unroll
;                 for (int m2 = 0; m2 < 2; ++m2) {
;                     const int m = 2 * mp + m2;
;                     const int r = rbase + 16 * m;
;                     float ss = 0.f;
; #pragma unroll
;                     for (int bj = 0; bj < 2; ++bj) {
;                         const int c0 = c00 + bj * 128;
;                         float* xn = xdst + (size_t)r * DM + c0;
;                         const f32x4 y0 = xv[m2][bj][0] + gt[bj][0] * acc[ai][bj][m][0], y1 = xv[m2][bj][1] + gt[bj][1] * acc[ai][bj][m][1];
;                         *(f32x4*)xn = y0; *(f32x4*)(xn + 4) = y1;
;                         if (Hn) {
;                             ss += y0[0] * y0[0] + y0[1] * y0[1] + y0[2] * y0[2] + y0[3] * y0[3] + y1[0] * y1[0] + y1[1] * y1[1] + y1[2] * y1[2] + y1[3] * y1[3];
;                             const f32x4 h0 = y0 * gh[bj][0], h1 = y1 * gh[bj][1];
;                             u32x4 w; w.x = cvtpk(h0[0], h0[1]); w.y = cvtpk(h0[2], h0[3]); w.z = cvtpk(h1[0], h1[1]); w.w = cvtpk(h1[2], h1[3]);
;                             *(u32x4*)(Hn + (size_t)r * DM + c0) = w;
;                         }
;                     }
;                     if (Hn) {
;                         ss += __shfl_xor(ss, 16); ss += __shfl_xor(ss, 32);
;                         if (fq == 0) atomicAdd(rsn + r, ss);
;                     }
.LBB0_1492:
	v_lshlrev_b64 v[36:37], 12, v[36:37]
	v_lshl_add_u64 v[34:35], v[34:35], 0, v[36:37]
	v_lshl_add_u64 v[38:39], v[34:35], 0, v[208:209]
	global_load_dwordx4 v[42:45], v[38:39], off offset:16
	global_load_dwordx4 v[50:53], v[38:39], off
	global_load_dwordx4 v[34:37], v[38:39], off offset:528
	s_nop 0
	global_load_dwordx4 v[38:41], v[38:39], off offset:512
	s_waitcnt vmcnt(6)
	v_pk_fma_f32 v[30:31], v[30:31], v[78:79], v[62:63]
	v_pk_fma_f32 v[28:29], v[28:29], v[76:77], v[60:61]
	v_mul_f32_e32 v60, v31, v31
	v_pk_fma_f32 v[32:33], v[32:33], v[80:81], v[64:65]
	v_fmac_f32_e32 v60, v30, v30
	v_fmac_f32_e32 v60, v32, v32
	v_lshlrev_b64 v[88:89], 12, v[84:85]
	v_pk_fma_f32 v[26:27], v[26:27], v[74:75], v[58:59]
	v_fmac_f32_e32 v60, v33, v33
	v_lshl_add_u64 v[88:89], s[92:93], 0, v[88:89]
	v_fmac_f32_e32 v60, v26, v26
	v_lshl_add_u64 v[88:89], v[88:89], 0, v[208:209]
	v_fmac_f32_e32 v60, v27, v27
	global_store_dwordx4 v[88:89], v[30:33], off nt
	global_store_dwordx4 v[88:89], v[26:29], off offset:16 nt
	v_fmac_f32_e32 v60, v28, v28
	v_pk_mul_f32 v[30:31], v[128:129], v[30:31]
	v_fmac_f32_e32 v60, v29, v29
	v_pk_mul_f32 v[58:59], v[130:131], v[28:29]
	v_pk_mul_f32 v[28:29], v[132:133], v[26:27]
	v_cvt_pk_bf16_f32 v26, v30, v31
	v_lshlrev_b64 v[30:31], 11, v[84:85]
	v_pk_mul_f32 v[32:33], v[126:127], v[32:33]
	v_lshl_add_u64 v[30:31], s[80:81], 0, v[30:31]
	v_cvt_pk_bf16_f32 v27, v32, v33
	v_cvt_pk_bf16_f32 v28, v28, v29
	v_cvt_pk_bf16_f32 v29, v58, v59
	v_lshl_add_u64 v[30:31], v[206:207], 1, v[30:31]
	s_waitcnt vmcnt(6)
	v_pk_fma_f32 v[22:23], v[22:23], v[70:71], v[54:55]
	global_store_dwordx4 v[30:31], v[26:29], off
	v_pk_fma_f32 v[24:25], v[24:25], v[72:73], v[56:57]
	v_pk_fma_f32 v[18:19], v[18:19], v[66:67], v[46:47]
	v_mul_f32_e32 v28, v23, v23
	v_fmac_f32_e32 v28, v22, v22
	v_fmac_f32_e32 v28, v24, v24
	v_fmac_f32_e32 v28, v25, v25
	v_fmac_f32_e32 v28, v18, v18
	v_pk_fma_f32 v[20:21], v[20:21], v[68:69], v[48:49]
	v_fmac_f32_e32 v28, v19, v19
	v_fmac_f32_e32 v28, v20, v20
	v_fmac_f32_e32 v28, v21, v21
	v_add_f32_e32 v32, v60, v28
	ds_bpermute_b32 v33, v156, v32
	global_store_dwordx4 v[88:89], v[22:25], off offset:512 nt
	global_store_dwordx4 v[88:89], v[18:21], off offset:528 nt
	v_pk_mul_f32 v[28:29], v[118:119], v[18:19]
	v_pk_mul_f32 v[26:27], v[120:121], v[24:25]
	v_pk_mul_f32 v[22:23], v[114:115], v[22:23]
	s_waitcnt lgkmcnt(0)
	v_add_f32_e32 v18, v32, v33
	ds_bpermute_b32 v19, v157, v18
	v_pk_mul_f32 v[24:25], v[116:117], v[20:21]
	v_cvt_pk_bf16_f32 v20, v22, v23
	v_cvt_pk_bf16_f32 v21, v26, v27
	v_cvt_pk_bf16_f32 v22, v28, v29
	v_cvt_pk_bf16_f32 v23, v24, v25
	global_store_dwordx4 v[30:31], v[20:23], off offset:256
	s_and_saveexec_b64 s[2:3], s[38:39]
	s_cbranch_execz .LBB0_1494
	s_waitcnt lgkmcnt(0)
	v_add_f32_e32 v18, v18, v19
	global_atomic_add_f32 v[86:87], v18, off offset:128
.LBB0_1494:
	s_or_b64 exec, exec, s[2:3]
	s_waitcnt vmcnt(8)
	v_pk_fma_f32 v[14:15], v[14:15], v[78:79], v[50:51]
	v_pk_fma_f32 v[16:17], v[16:17], v[80:81], v[52:53]
	v_mul_f32_e32 v22, v15, v15
	v_fmac_f32_e32 v22, v14, v14
	v_fmac_f32_e32 v22, v16, v16
	s_waitcnt lgkmcnt(0)
	v_lshlrev_b64 v[18:19], 12, v[82:83]
	v_pk_fma_f32 v[10:11], v[10:11], v[74:75], v[42:43]
	v_fmac_f32_e32 v22, v17, v17
	v_lshl_add_u64 v[18:19], s[92:93], 0, v[18:19]
	v_fmac_f32_e32 v22, v10, v10
	v_lshl_add_u64 v[18:19], v[206:207], 2, v[18:19]
	v_pk_fma_f32 v[12:13], v[12:13], v[76:77], v[44:45]
	v_fmac_f32_e32 v22, v11, v11
	global_store_dwordx4 v[18:19], v[14:17], off nt
	global_store_dwordx4 v[18:19], v[10:13], off offset:16 nt
	v_fmac_f32_e32 v22, v12, v12
	v_pk_mul_f32 v[14:15], v[128:129], v[14:15]
	v_fmac_f32_e32 v22, v13, v13
	v_pk_mul_f32 v[20:21], v[130:131], v[12:13]
	v_pk_mul_f32 v[12:13], v[132:133], v[10:11]
	v_cvt_pk_bf16_f32 v10, v14, v15
	v_lshlrev_b64 v[14:15], 11, v[82:83]
	v_pk_mul_f32 v[16:17], v[126:127], v[16:17]
	v_lshl_add_u64 v[14:15], s[80:81], 0, v[14:15]
	v_cvt_pk_bf16_f32 v11, v16, v17
	v_cvt_pk_bf16_f32 v12, v12, v13
	v_cvt_pk_bf16_f32 v13, v20, v21
	v_lshl_add_u64 v[14:15], v[206:207], 1, v[14:15]
	s_waitcnt vmcnt(8)
	v_pk_fma_f32 v[6:7], v[6:7], v[70:71], v[38:39]
	global_store_dwordx4 v[14:15], v[10:13], off
	v_pk_fma_f32 v[8:9], v[8:9], v[72:73], v[40:41]
	v_pk_fma_f32 v[0:1], v[0:1], v[66:67], v[34:35]
	v_mul_f32_e32 v12, v7, v7
	v_fmac_f32_e32 v12, v6, v6
	v_fmac_f32_e32 v12, v8, v8
	v_fmac_f32_e32 v12, v9, v9
	v_fmac_f32_e32 v12, v0, v0
	v_pk_fma_f32 v[2:3], v[2:3], v[68:69], v[36:37]
	v_fmac_f32_e32 v12, v1, v1
	v_fmac_f32_e32 v12, v2, v2
	v_fmac_f32_e32 v12, v3, v3
	v_add_f32_e32 v12, v22, v12
	ds_bpermute_b32 v13, v156, v12
	global_store_dwordx4 v[18:19], v[6:9], off offset:512 nt
	global_store_dwordx4 v[18:19], v[0:3], off offset:528 nt
	v_pk_mul_f32 v[10:11], v[120:121], v[8:9]
	v_pk_mul_f32 v[8:9], v[118:119], v[0:1]
	v_pk_mul_f32 v[6:7], v[114:115], v[6:7]
	s_waitcnt lgkmcnt(0)
	v_add_f32_e32 v0, v12, v13
	ds_bpermute_b32 v1, v157, v0
	v_pk_mul_f32 v[2:3], v[116:117], v[2:3]
	v_cvt_pk_bf16_f32 v6, v6, v7
	v_cvt_pk_bf16_f32 v7, v10, v11
	v_cvt_pk_bf16_f32 v8, v8, v9
	v_cvt_pk_bf16_f32 v9, v2, v3
	global_store_dwordx4 v[14:15], v[6:9], off offset:256
	s_and_saveexec_b64 s[2:3], s[38:39]
	s_cbranch_execz .LBB0_1496
	s_waitcnt lgkmcnt(0)
	v_add_f32_e32 v0, v0, v1
	global_atomic_add_f32 v[86:87], v0, off offset:192

; __device__ __forceinline__ unsigned cvtpk(float lo, float hi) { f32x2_t v = {lo, hi}; bf16x2_t b = __builtin_convertvector(v, bf16x2_t); return __builtin_bit_cast(unsigned, b); }
;     __device__ __forceinline__ void operator()(const f32x4 (&acc)[2][2][4][2], const Unit& u, int wr, int wc, int fr, int fq) const {
;     ...
;                 for (int m2 = 0; m2 < 2; ++m2) {
;                     const int r = rbase + 16 * (2 * mp + m2);
;                     const float* xo = from_input ? ((r < MP) ? xp + (size_t)r * DM : xs + (size_t)(r - MP) * DM) : xbuf + (size_t)r * DM;
; #pragma unroll
;                     for (int bj = 0; bj < 2; ++bj) { xv[m2][bj][0] = *(const f32x4*)(xo + c00 + bj * 128); xv[m2][bj][1] = *(const f32x4*)(xo + c00 + bj * 128 + 4); }
;                 }
; #pragma unroll
;                 for (int m2 = 0; m2 < 2; ++m2) {
;                     const int m = 2 * mp + m2;
;                     const int r = rbase + 16 * m;
;                     float ss = 0.f;
; #pragma unroll
;                     for (int bj = 0; bj < 2; ++bj) {
;                         const int c0 = c00 + bj * 128;
;                         float* xn = xdst + (size_t)r * DM + c0;
;                         const f32x4 y0 = xv[m2][bj][0] + gt[bj][0] * acc[ai][bj][m][0], y1 = xv[m2][bj][1] + gt[bj][1] * acc[ai][bj][m][1];
;                         *(f32x4*)xn = y0; *(f32x4*)(xn + 4) = y1;
;                         if (Hn) {
;                             ss += y0[0] * y0[0] + y0[1] * y0[1] + y0[2] * y0[2] + y0[3] * y0[3] + y1[0] * y1[0] + y1[1] * y1[1] + y1[2] * y1[2] + y1[3] * y1[3];
;                             const f32x4 h0 = y0 * gh[bj][0], h1 = y1 * gh[bj][1];
;                             u32x4 w; w.x = cvtpk(h0[0], h0[1]); w.y = cvtpk(h0[2], h0[3]); w.z = cvtpk(h1[0], h1[1]); w.w = cvtpk(h1[2], h1[3]);
;                             *(u32x4*)(Hn + (size_t)r * DM + c0) = w;
;                         }
;                     }
;                     if (Hn) {
;                         ss += __shfl_xor(ss, 16); ss += __shfl_xor(ss, 32);
;                         if (fq == 0) atomicAdd(rsn + r, ss);
;                     }
.LBB0_1865:
	v_ashrrev_i32_e32 v241, 31, v240
	v_lshlrev_b64 v[182:183], 12, v[240:241]
	v_or_b32_e32 v242, 16, v240
	v_lshl_add_u64 v[182:183], s[92:93], 0, v[182:183]
	v_ashrrev_i32_e32 v243, 31, v242
	v_lshl_add_u64 v[246:247], v[182:183], 0, v[236:237]
	v_lshlrev_b64 v[182:183], 12, v[242:243]
	v_lshl_add_u64 v[182:183], s[92:93], 0, v[182:183]
	v_lshl_add_u64 v[244:245], v[182:183], 0, v[236:237]
	global_load_dwordx4 v[206:209], v[246:247], off offset:16
	global_load_dwordx4 v[210:213], v[246:247], off
	global_load_dwordx4 v[198:201], v[246:247], off offset:528
	global_load_dwordx4 v[202:205], v[246:247], off offset:512
	global_load_dwordx4 v[190:193], v[244:245], off offset:16
	global_load_dwordx4 v[194:197], v[244:245], off
	global_load_dwordx4 v[182:185], v[244:245], off offset:528
	global_load_dwordx4 v[186:189], v[244:245], off offset:512
	s_mov_b64 s[2:3], -1
	s_and_b64 vcc, exec, s[72:73]
	s_waitcnt vmcnt(0)
	v_pk_fma_f32 v[208:209], v[164:165], v[176:177], v[208:209]
	v_pk_fma_f32 v[212:213], v[160:161], v[180:181], v[212:213]
	v_pk_fma_f32 v[210:211], v[158:159], v[178:179], v[210:211]
	v_pk_fma_f32 v[206:207], v[162:163], v[174:175], v[206:207]
	v_pk_fma_f32 v[162:163], v[154:155], v[170:171], v[202:203]
	v_pk_fma_f32 v[158:159], v[150:151], v[166:167], v[198:199]
	global_store_dwordx4 v[246:247], v[210:213], off nt
	global_store_dwordx4 v[246:247], v[206:209], off offset:16 nt
	s_cbranch_vccz .LBB0_1867
	v_pk_fma_f32 v[164:165], v[156:157], v[172:173], v[204:205]
	v_pk_fma_f32 v[160:161], v[152:153], v[168:169], v[200:201]
	global_store_dwordx4 v[246:247], v[162:165], off offset:512 nt
	global_store_dwordx4 v[246:247], v[158:161], off offset:528 nt
	s_mov_b64 s[2:3], 0
.LBB0_1867:
	s_andn2_b64 vcc, exec, s[2:3]
	s_cbranch_vccnz .LBB0_1871
	v_mul_f32_e32 v30, v211, v211
	v_fmac_f32_e32 v30, v210, v210
	v_fmac_f32_e32 v30, v212, v212
	v_fmac_f32_e32 v30, v213, v213
	v_fmac_f32_e32 v30, v206, v206
	v_fmac_f32_e32 v30, v207, v207
	v_pk_mul_f32 v[164:165], v[10:11], v[206:207]
	v_mul_f32_e32 v39, v163, v163
	v_fmac_f32_e32 v30, v208, v208
	v_pk_mul_f32 v[160:161], v[12:13], v[208:209]
	v_cvt_pk_bf16_f32 v208, v164, v165
	v_pk_fma_f32 v[164:165], v[156:157], v[172:173], v[204:205]
	v_fmac_f32_e32 v39, v162, v162
	v_fmac_f32_e32 v39, v164, v164
	v_fmac_f32_e32 v39, v165, v165
	v_pk_mul_f32 v[150:151], v[8:9], v[212:213]
	v_fmac_f32_e32 v39, v158, v158
	v_fmac_f32_e32 v30, v209, v209
	v_cvt_pk_bf16_f32 v207, v150, v151
	v_cvt_pk_bf16_f32 v209, v160, v161
	v_lshlrev_b64 v[150:151], 11, v[240:241]
	v_pk_fma_f32 v[160:161], v[152:153], v[168:169], v[200:201]
	v_fmac_f32_e32 v39, v159, v159
	v_pk_mul_f32 v[154:155], v[6:7], v[210:211]
	v_lshl_add_u64 v[150:151], s[80:81], 0, v[150:151]
	v_fmac_f32_e32 v39, v160, v160
	v_cvt_pk_bf16_f32 v206, v154, v155
	v_lshl_add_u64 v[154:155], v[234:235], 1, v[150:151]
	v_fmac_f32_e32 v39, v161, v161
	v_and_b32_e32 v150, 64, v248
	global_store_dwordx4 v[154:155], v[206:209], off
	global_store_dwordx4 v[246:247], v[162:165], off offset:512 nt
	global_store_dwordx4 v[246:247], v[158:161], off offset:528 nt
	v_pk_mul_f32 v[152:153], v[16:17], v[164:165]
	v_add_f32_e32 v30, v30, v39
	v_xor_b32_e32 v39, 16, v248
	v_add_u32_e32 v164, 64, v150
	v_cmp_lt_i32_e32 vcc, v39, v164
	v_pk_mul_f32 v[150:151], v[14:15], v[162:163]
	v_pk_mul_f32 v[156:157], v[20:21], v[160:161]
	v_cndmask_b32_e32 v39, v248, v39, vcc
	v_lshlrev_b32_e32 v39, 2, v39
	ds_bpermute_b32 v39, v39, v30
	v_pk_mul_f32 v[158:159], v[18:19], v[158:159]
	v_cvt_pk_bf16_f32 v150, v150, v151
	v_cvt_pk_bf16_f32 v151, v152, v153
	v_cvt_pk_bf16_f32 v152, v158, v159
	s_waitcnt lgkmcnt(0)
	v_add_f32_e32 v30, v30, v39
	v_xor_b32_e32 v39, 32, v248
	v_cmp_lt_i32_e32 vcc, v39, v164
	v_cvt_pk_bf16_f32 v153, v156, v157
	global_store_dwordx4 v[154:155], v[150:153], off offset:256
	v_cndmask_b32_e32 v39, v248, v39, vcc
	v_lshlrev_b32_e32 v39, 2, v39
	ds_bpermute_b32 v39, v39, v30
	s_and_saveexec_b64 s[2:3], s[38:39]
	s_cbranch_execz .LBB0_1870
	v_readlane_b32 s30, v251, 45
	v_readlane_b32 s31, v251, 46
	s_waitcnt lgkmcnt(0)
	v_add_f32_e32 v30, v30, v39
	v_lshl_add_u64 v[150:151], v[240:241], 2, s[30:31]
	global_atomic_add_f32 v[150:151], v30, off

; __device__ __forceinline__ unsigned cvtpk(float lo, float hi) { f32x2_t v = {lo, hi}; bf16x2_t b = __builtin_convertvector(v, bf16x2_t); return __builtin_bit_cast(unsigned, b); }
;     __device__ __forceinline__ void operator()(const f32x4 (&acc)[2][2][4][2], const Unit& u, int wr, int wc, int fr, int fq) const {
;     ...
;                 for (int m2 = 0; m2 < 2; ++m2) {
;                     const int m = 2 * mp + m2;
;                     const int r = rbase + 16 * m;
;                     float ss = 0.f;
; #pragma unroll
;                     for (int bj = 0; bj < 2; ++bj) {
;                         const int c0 = c00 + bj * 128;
;                         float* xn = xdst + (size_t)r * DM + c0;
;                         const f32x4 y0 = xv[m2][bj][0] + gt[bj][0] * acc[ai][bj][m][0], y1 = xv[m2][bj][1] + gt[bj][1] * acc[ai][bj][m][1];
;                         *(f32x4*)xn = y0; *(f32x4*)(xn + 4) = y1;
;                         if (Hn) {
;                             ss += y0[0] * y0[0] + y0[1] * y0[1] + y0[2] * y0[2] + y0[3] * y0[3] + y1[0] * y1[0] + y1[1] * y1[1] + y1[2] * y1[2] + y1[3] * y1[3];
;                             const f32x4 h0 = y0 * gh[bj][0], h1 = y1 * gh[bj][1];
;                             u32x4 w; w.x = cvtpk(h0[0], h0[1]); w.y = cvtpk(h0[2], h0[3]); w.z = cvtpk(h1[0], h1[1]); w.w = cvtpk(h1[2], h1[3]);
;                             *(u32x4*)(Hn + (size_t)r * DM + c0) = w;
;                         }
;                     }
;                     if (Hn) {
;                         ss += __shfl_xor(ss, 16); ss += __shfl_xor(ss, 32);
;                         if (fq == 0) atomicAdd(rsn + r, ss);
;                     }
.LBB0_1871:
	v_pk_fma_f32 v[152:153], v[148:149], v[180:181], v[196:197]
	v_pk_fma_f32 v[150:151], v[146:147], v[178:179], v[194:195]
	v_pk_fma_f32 v[156:157], v[144:145], v[176:177], v[192:193]
	v_pk_fma_f32 v[154:155], v[142:143], v[174:175], v[190:191]
	s_mov_b64 s[2:3], -1
	s_and_b64 vcc, exec, s[72:73]
	v_pk_fma_f32 v[146:147], v[138:139], v[170:171], v[186:187]
	v_pk_fma_f32 v[142:143], v[134:135], v[166:167], v[182:183]
	global_store_dwordx4 v[244:245], v[150:153], off nt
	global_store_dwordx4 v[244:245], v[154:157], off offset:16 nt
	s_cbranch_vccz .LBB0_1873
	v_pk_fma_f32 v[148:149], v[140:141], v[172:173], v[188:189]
	v_pk_fma_f32 v[144:145], v[136:137], v[168:169], v[184:185]
	global_store_dwordx4 v[244:245], v[146:149], off offset:512 nt
	global_store_dwordx4 v[244:245], v[142:145], off offset:528 nt
	s_mov_b64 s[2:3], 0
.LBB0_1873:
	s_andn2_b64 vcc, exec, s[2:3]
	s_cbranch_vccnz .LBB0_1877
	v_pk_mul_f32 v[134:135], v[8:9], v[152:153]
	v_mul_f32_e32 v30, v151, v151
	v_cvt_pk_bf16_f32 v149, v134, v135
	v_lshlrev_b64 v[134:135], 11, v[242:243]
	v_fmac_f32_e32 v30, v150, v150
	v_pk_mul_f32 v[138:139], v[6:7], v[150:151]
	v_pk_mul_f32 v[144:145], v[12:13], v[156:157]
	v_pk_mul_f32 v[150:151], v[10:11], v[154:155]
	v_lshl_add_u64 v[134:135], s[80:81], 0, v[134:135]
	v_cvt_pk_bf16_f32 v148, v138, v139
	v_cvt_pk_bf16_f32 v150, v150, v151
	v_cvt_pk_bf16_f32 v151, v144, v145
	v_lshl_add_u64 v[138:139], v[234:235], 1, v[134:135]
	s_waitcnt lgkmcnt(0)
	v_mul_f32_e32 v39, v147, v147
	global_store_dwordx4 v[138:139], v[148:151], off
	v_fmac_f32_e32 v39, v146, v146
	v_fmac_f32_e32 v30, v152, v152
	v_pk_fma_f32 v[148:149], v[140:141], v[172:173], v[188:189]
	v_fmac_f32_e32 v30, v153, v153
	v_fmac_f32_e32 v39, v148, v148
	v_fmac_f32_e32 v39, v149, v149
	v_fmac_f32_e32 v30, v154, v154
	v_fmac_f32_e32 v39, v142, v142
	v_fmac_f32_e32 v30, v155, v155
	v_pk_fma_f32 v[144:145], v[136:137], v[168:169], v[184:185]
	v_fmac_f32_e32 v39, v143, v143
	v_fmac_f32_e32 v30, v156, v156
	v_fmac_f32_e32 v39, v144, v144
	v_fmac_f32_e32 v30, v157, v157
	v_fmac_f32_e32 v39, v145, v145
	v_and_b32_e32 v134, 64, v248
	global_store_dwordx4 v[244:245], v[146:149], off offset:512 nt
	global_store_dwordx4 v[244:245], v[142:145], off offset:528 nt
	v_pk_mul_f32 v[136:137], v[16:17], v[148:149]
	v_add_f32_e32 v30, v30, v39
	v_xor_b32_e32 v39, 16, v248
	v_add_u32_e32 v148, 64, v134
	v_cmp_lt_i32_e32 vcc, v39, v148
	v_pk_mul_f32 v[134:135], v[14:15], v[146:147]
	v_pk_mul_f32 v[140:141], v[20:21], v[144:145]
	v_cndmask_b32_e32 v39, v248, v39, vcc
	v_lshlrev_b32_e32 v39, 2, v39
	ds_bpermute_b32 v39, v39, v30
	v_pk_mul_f32 v[142:143], v[18:19], v[142:143]
	v_cvt_pk_bf16_f32 v134, v134, v135
	v_cvt_pk_bf16_f32 v135, v136, v137
	v_cvt_pk_bf16_f32 v136, v142, v143
	s_waitcnt lgkmcnt(0)
	v_add_f32_e32 v30, v30, v39
	v_xor_b32_e32 v39, 32, v248
	v_cmp_lt_i32_e32 vcc, v39, v148
	v_cvt_pk_bf16_f32 v137, v140, v141
	global_store_dwordx4 v[138:139], v[134:137], off offset:256
	v_cndmask_b32_e32 v39, v248, v39, vcc
	v_lshlrev_b32_e32 v39, 2, v39
	ds_bpermute_b32 v39, v39, v30
	s_and_saveexec_b64 s[2:3], s[38:39]
	s_cbranch_execz .LBB0_1876
	v_readlane_b32 s30, v251, 45
	v_readlane_b32 s31, v251, 46
	s_waitcnt lgkmcnt(0)
	v_add_f32_e32 v30, v30, v39
	v_lshl_add_u64 v[134:135], v[242:243], 2, s[30:31]
	global_atomic_add_f32 v[134:135], v30, off

; __device__ __forceinline__ unsigned cvtpk(float lo, float hi) { f32x2_t v = {lo, hi}; bf16x2_t b = __builtin_convertvector(v, bf16x2_t); return __builtin_bit_cast(unsigned, b); }
;     __device__ __forceinline__ void operator()(const f32x4 (&acc)[2][2][4][2], const Unit& u, int wr, int wc, int fr, int fq) const {
;     ...
;                 for (int m2 = 0; m2 < 2; ++m2) {
;                     const int r = rbase + 16 * (2 * mp + m2);
;                     const float* xo = from_input ? ((r < MP) ? xp + (size_t)r * DM : xs + (size_t)(r - MP) * DM) : xbuf + (size_t)r * DM;
; #pragma unroll
;                     for (int bj = 0; bj < 2; ++bj) { xv[m2][bj][0] = *(const f32x4*)(xo + c00 + bj * 128); xv[m2][bj][1] = *(const f32x4*)(xo + c00 + bj * 128 + 4); }
;                 }
; #pragma unroll
;                 for (int m2 = 0; m2 < 2; ++m2) {
;                     const int m = 2 * mp + m2;
;                     const int r = rbase + 16 * m;
;                     float ss = 0.f;
; #pragma unroll
;                     for (int bj = 0; bj < 2; ++bj) {
;                         const int c0 = c00 + bj * 128;
;                         float* xn = xdst + (size_t)r * DM + c0;
;                         const f32x4 y0 = xv[m2][bj][0] + gt[bj][0] * acc[ai][bj][m][0], y1 = xv[m2][bj][1] + gt[bj][1] * acc[ai][bj][m][1];
;                         *(f32x4*)xn = y0; *(f32x4*)(xn + 4) = y1;
;                         if (Hn) {
;                             ss += y0[0] * y0[0] + y0[1] * y0[1] + y0[2] * y0[2] + y0[3] * y0[3] + y1[0] * y1[0] + y1[1] * y1[1] + y1[2] * y1[2] + y1[3] * y1[3];
;                             const f32x4 h0 = y0 * gh[bj][0], h1 = y1 * gh[bj][1];
;                             u32x4 w; w.x = cvtpk(h0[0], h0[1]); w.y = cvtpk(h0[2], h0[3]); w.z = cvtpk(h1[0], h1[1]); w.w = cvtpk(h1[2], h1[3]);
;                             *(u32x4*)(Hn + (size_t)r * DM + c0) = w;
;                         }
;                     }
;                     if (Hn) {
;                         ss += __shfl_xor(ss, 16); ss += __shfl_xor(ss, 32);
;                         if (fq == 0) atomicAdd(rsn + r, ss);
;                     }
.LBB0_1877:
	v_or_b32_e32 v186, 32, v240
	v_ashrrev_i32_e32 v187, 31, v186
	v_lshlrev_b64 v[134:135], 12, v[186:187]
	v_or_b32_e32 v182, 48, v240
	v_lshl_add_u64 v[134:135], s[92:93], 0, v[134:135]
	v_ashrrev_i32_e32 v183, 31, v182
	v_lshl_add_u64 v[188:189], v[134:135], 0, v[236:237]
	v_lshlrev_b64 v[134:135], 12, v[182:183]
	v_lshl_add_u64 v[134:135], s[92:93], 0, v[134:135]
	v_lshl_add_u64 v[184:185], v[134:135], 0, v[236:237]
	global_load_dwordx4 v[158:161], v[188:189], off offset:16
	global_load_dwordx4 v[162:165], v[188:189], off
	global_load_dwordx4 v[150:153], v[188:189], off offset:528
	global_load_dwordx4 v[154:157], v[188:189], off offset:512
	global_load_dwordx4 v[142:145], v[184:185], off offset:16
	global_load_dwordx4 v[146:149], v[184:185], off
	global_load_dwordx4 v[134:137], v[184:185], off offset:528
	global_load_dwordx4 v[138:141], v[184:185], off offset:512
	s_mov_b64 s[2:3], -1
	s_and_b64 vcc, exec, s[72:73]
	s_waitcnt vmcnt(0)
	v_pk_fma_f32 v[160:161], v[128:129], v[176:177], v[160:161]
	v_pk_fma_f32 v[164:165], v[132:133], v[180:181], v[164:165]
	v_pk_fma_f32 v[162:163], v[130:131], v[178:179], v[162:163]
	v_pk_fma_f32 v[158:159], v[126:127], v[174:175], v[158:159]
	v_pk_fma_f32 v[130:131], v[122:123], v[170:171], v[154:155]
	v_pk_fma_f32 v[126:127], v[118:119], v[166:167], v[150:151]
	global_store_dwordx4 v[188:189], v[162:165], off nt
	global_store_dwordx4 v[188:189], v[158:161], off offset:16 nt
	s_cbranch_vccz .LBB0_1879
	v_pk_fma_f32 v[132:133], v[124:125], v[172:173], v[156:157]
	v_pk_fma_f32 v[128:129], v[120:121], v[168:169], v[152:153]
	global_store_dwordx4 v[188:189], v[130:133], off offset:512 nt
	global_store_dwordx4 v[188:189], v[126:129], off offset:528 nt
	s_mov_b64 s[2:3], 0
.LBB0_1879:
	s_andn2_b64 vcc, exec, s[2:3]
	s_cbranch_vccnz .LBB0_1883
	v_mul_f32_e32 v30, v163, v163
	v_fmac_f32_e32 v30, v162, v162
	v_fmac_f32_e32 v30, v164, v164
	v_fmac_f32_e32 v30, v165, v165
	v_fmac_f32_e32 v30, v158, v158
	v_fmac_f32_e32 v30, v159, v159
	v_pk_mul_f32 v[132:133], v[10:11], v[158:159]
	s_waitcnt lgkmcnt(0)
	v_mul_f32_e32 v39, v131, v131
	v_fmac_f32_e32 v30, v160, v160
	v_pk_mul_f32 v[128:129], v[12:13], v[160:161]
	v_cvt_pk_bf16_f32 v160, v132, v133
	v_pk_fma_f32 v[132:133], v[124:125], v[172:173], v[156:157]
	v_fmac_f32_e32 v39, v130, v130
	v_fmac_f32_e32 v39, v132, v132
	v_fmac_f32_e32 v39, v133, v133
	v_pk_mul_f32 v[118:119], v[8:9], v[164:165]
	v_fmac_f32_e32 v39, v126, v126
	v_fmac_f32_e32 v30, v161, v161
	v_cvt_pk_bf16_f32 v159, v118, v119
	v_cvt_pk_bf16_f32 v161, v128, v129
	v_lshlrev_b64 v[118:119], 11, v[186:187]
	v_pk_fma_f32 v[128:129], v[120:121], v[168:169], v[152:153]
	v_fmac_f32_e32 v39, v127, v127
	v_pk_mul_f32 v[122:123], v[6:7], v[162:163]
	v_lshl_add_u64 v[118:119], s[80:81], 0, v[118:119]
	v_fmac_f32_e32 v39, v128, v128
	v_cvt_pk_bf16_f32 v158, v122, v123
	v_lshl_add_u64 v[122:123], v[234:235], 1, v[118:119]
	v_fmac_f32_e32 v39, v129, v129
	v_and_b32_e32 v118, 64, v248
	global_store_dwordx4 v[122:123], v[158:161], off
	global_store_dwordx4 v[188:189], v[130:133], off offset:512 nt
	global_store_dwordx4 v[188:189], v[126:129], off offset:528 nt
	v_pk_mul_f32 v[120:121], v[16:17], v[132:133]
	v_add_f32_e32 v30, v30, v39
	v_xor_b32_e32 v39, 16, v248
	v_add_u32_e32 v132, 64, v118
	v_cmp_lt_i32_e32 vcc, v39, v132
	v_pk_mul_f32 v[118:119], v[14:15], v[130:131]
	v_pk_mul_f32 v[124:125], v[20:21], v[128:129]
	v_cndmask_b32_e32 v39, v248, v39, vcc
	v_lshlrev_b32_e32 v39, 2, v39
	ds_bpermute_b32 v39, v39, v30
	v_pk_mul_f32 v[126:127], v[18:19], v[126:127]
	v_cvt_pk_bf16_f32 v118, v118, v119
	v_cvt_pk_bf16_f32 v119, v120, v121
	v_cvt_pk_bf16_f32 v120, v126, v127
	s_waitcnt lgkmcnt(0)
	v_add_f32_e32 v30, v30, v39
	v_xor_b32_e32 v39, 32, v248
	v_cmp_lt_i32_e32 vcc, v39, v132
	v_cvt_pk_bf16_f32 v121, v124, v125
	global_store_dwordx4 v[122:123], v[118:121], off offset:256
	v_cndmask_b32_e32 v39, v248, v39, vcc
	v_lshlrev_b32_e32 v39, 2, v39
	ds_bpermute_b32 v39, v39, v30
	s_and_saveexec_b64 s[2:3], s[38:39]
	s_cbranch_execz .LBB0_1882
	v_readlane_b32 s30, v251, 45
	v_readlane_b32 s31, v251, 46
	s_waitcnt lgkmcnt(0)
	v_add_f32_e32 v30, v30, v39
	v_lshl_add_u64 v[118:119], v[186:187], 2, s[30:31]
	global_atomic_add_f32 v[118:119], v30, off

; __device__ __forceinline__ unsigned cvtpk(float lo, float hi) { f32x2_t v = {lo, hi}; bf16x2_t b = __builtin_convertvector(v, bf16x2_t); return __builtin_bit_cast(unsigned, b); }
;     __device__ __forceinline__ void operator()(const f32x4 (&acc)[2][2][4][2], const Unit& u, int wr, int wc, int fr, int fq) const {
;     ...
;                 for (int m2 = 0; m2 < 2; ++m2) {
;                     const int m = 2 * mp + m2;
;                     const int r = rbase + 16 * m;
;                     float ss = 0.f;
; #pragma unroll
;                     for (int bj = 0; bj < 2; ++bj) {
;                         const int c0 = c00 + bj * 128;
;                         float* xn = xdst + (size_t)r * DM + c0;
;                         const f32x4 y0 = xv[m2][bj][0] + gt[bj][0] * acc[ai][bj][m][0], y1 = xv[m2][bj][1] + gt[bj][1] * acc[ai][bj][m][1];
;                         *(f32x4*)xn = y0; *(f32x4*)(xn + 4) = y1;
;                         if (Hn) {
;                             ss += y0[0] * y0[0] + y0[1] * y0[1] + y0[2] * y0[2] + y0[3] * y0[3] + y1[0] * y1[0] + y1[1] * y1[1] + y1[2] * y1[2] + y1[3] * y1[3];
;                             const f32x4 h0 = y0 * gh[bj][0], h1 = y1 * gh[bj][1];
;                             u32x4 w; w.x = cvtpk(h0[0], h0[1]); w.y = cvtpk(h0[2], h0[3]); w.z = cvtpk(h1[0], h1[1]); w.w = cvtpk(h1[2], h1[3]);
;                             *(u32x4*)(Hn + (size_t)r * DM + c0) = w;
;                         }
;                     }
;                     if (Hn) {
;                         ss += __shfl_xor(ss, 16); ss += __shfl_xor(ss, 32);
;                         if (fq == 0) atomicAdd(rsn + r, ss);
;                     }
.LBB0_1883:
	v_pk_fma_f32 v[120:121], v[116:117], v[180:181], v[148:149]
	v_pk_fma_f32 v[118:119], v[114:115], v[178:179], v[146:147]
	v_pk_fma_f32 v[124:125], v[112:113], v[176:177], v[144:145]
	v_pk_fma_f32 v[122:123], v[110:111], v[174:175], v[142:143]
	s_mov_b64 s[2:3], -1
	s_and_b64 vcc, exec, s[72:73]
	v_pk_fma_f32 v[114:115], v[106:107], v[170:171], v[138:139]
	v_pk_fma_f32 v[110:111], v[40:41], v[166:167], v[134:135]
	global_store_dwordx4 v[184:185], v[118:121], off nt
	global_store_dwordx4 v[184:185], v[122:125], off offset:16 nt
	s_cbranch_vccz .LBB0_1885
	v_pk_fma_f32 v[116:117], v[108:109], v[172:173], v[140:141]
	v_pk_fma_f32 v[112:113], v[42:43], v[168:169], v[136:137]
	global_store_dwordx4 v[184:185], v[114:117], off offset:512 nt
	global_store_dwordx4 v[184:185], v[110:113], off offset:528 nt
	s_mov_b64 s[2:3], 0
.LBB0_1885:
	s_andn2_b64 vcc, exec, s[2:3]
	s_cbranch_vccnz .LBB0_1889
	v_pk_mul_f32 v[40:41], v[8:9], v[120:121]
	v_mul_f32_e32 v30, v119, v119
	v_cvt_pk_bf16_f32 v117, v40, v41
	v_lshlrev_b64 v[40:41], 11, v[182:183]
	v_fmac_f32_e32 v30, v118, v118
	v_pk_mul_f32 v[106:107], v[6:7], v[118:119]
	v_pk_mul_f32 v[112:113], v[12:13], v[124:125]
	v_pk_mul_f32 v[118:119], v[10:11], v[122:123]
	v_lshl_add_u64 v[40:41], s[80:81], 0, v[40:41]
	v_cvt_pk_bf16_f32 v116, v106, v107
	v_cvt_pk_bf16_f32 v118, v118, v119
	v_cvt_pk_bf16_f32 v119, v112, v113
	v_lshl_add_u64 v[106:107], v[234:235], 1, v[40:41]
	s_waitcnt lgkmcnt(0)
	v_mul_f32_e32 v39, v115, v115
	global_store_dwordx4 v[106:107], v[116:119], off
	v_fmac_f32_e32 v39, v114, v114
	v_fmac_f32_e32 v30, v120, v120
	v_pk_fma_f32 v[116:117], v[108:109], v[172:173], v[140:141]
	v_fmac_f32_e32 v30, v121, v121
	v_fmac_f32_e32 v39, v116, v116
	v_fmac_f32_e32 v39, v117, v117
	v_fmac_f32_e32 v30, v122, v122
	v_fmac_f32_e32 v39, v110, v110
	v_fmac_f32_e32 v30, v123, v123
	v_pk_fma_f32 v[112:113], v[42:43], v[168:169], v[136:137]
	v_fmac_f32_e32 v39, v111, v111
	v_fmac_f32_e32 v30, v124, v124
	v_fmac_f32_e32 v39, v112, v112
	v_fmac_f32_e32 v30, v125, v125
	v_fmac_f32_e32 v39, v113, v113
	v_and_b32_e32 v40, 64, v248
	global_store_dwordx4 v[184:185], v[114:117], off offset:512 nt
	global_store_dwordx4 v[184:185], v[110:113], off offset:528 nt
	v_pk_mul_f32 v[42:43], v[16:17], v[116:117]
	v_add_f32_e32 v30, v30, v39
	v_xor_b32_e32 v39, 16, v248
	v_add_u32_e32 v116, 64, v40
	v_cmp_lt_i32_e32 vcc, v39, v116
	v_pk_mul_f32 v[40:41], v[14:15], v[114:115]
	v_pk_mul_f32 v[108:109], v[20:21], v[112:113]
	v_cndmask_b32_e32 v39, v248, v39, vcc
	v_lshlrev_b32_e32 v39, 2, v39
	ds_bpermute_b32 v39, v39, v30
	v_pk_mul_f32 v[110:111], v[18:19], v[110:111]
	v_cvt_pk_bf16_f32 v40, v40, v41
	v_cvt_pk_bf16_f32 v41, v42, v43
	v_cvt_pk_bf16_f32 v42, v110, v111
	s_waitcnt lgkmcnt(0)
	v_add_f32_e32 v30, v30, v39
	v_xor_b32_e32 v39, 32, v248
	v_cmp_lt_i32_e32 vcc, v39, v116
	v_cvt_pk_bf16_f32 v43, v108, v109
	global_store_dwordx4 v[106:107], v[40:43], off offset:256
	v_cndmask_b32_e32 v39, v248, v39, vcc
	v_lshlrev_b32_e32 v39, 2, v39
	ds_bpermute_b32 v39, v39, v30
	s_and_saveexec_b64 s[2:3], s[38:39]
	s_cbranch_execz .LBB0_1888
	v_readlane_b32 s30, v251, 45
	v_readlane_b32 s31, v251, 46
	s_waitcnt lgkmcnt(0)
	v_add_f32_e32 v30, v30, v39
	v_lshl_add_u64 v[40:41], v[182:183], 2, s[30:31]
	global_atomic_add_f32 v[40:41], v30, off

; __device__ __forceinline__ unsigned cvtpk(float lo, float hi) { f32x2_t v = {lo, hi}; bf16x2_t b = __builtin_convertvector(v, bf16x2_t); return __builtin_bit_cast(unsigned, b); }
;     __device__ __forceinline__ void operator()(const f32x4 (&acc)[2][2][4][2], const Unit& u, int wr, int wc, int fr, int fq) const {
;     ...
;                 for (int m2 = 0; m2 < 2; ++m2) {
;                     const int r = rbase + 16 * (2 * mp + m2);
;                     const float* xo = from_input ? ((r < MP) ? xp + (size_t)r * DM : xs + (size_t)(r - MP) * DM) : xbuf + (size_t)r * DM;
; #pragma unroll
;                     for (int bj = 0; bj < 2; ++bj) { xv[m2][bj][0] = *(const f32x4*)(xo + c00 + bj * 128); xv[m2][bj][1] = *(const f32x4*)(xo + c00 + bj * 128 + 4); }
;                 }
; #pragma unroll
;                 for (int m2 = 0; m2 < 2; ++m2) {
;                     const int m = 2 * mp + m2;
;                     const int r = rbase + 16 * m;
;                     float ss = 0.f;
; #pragma unroll
;                     for (int bj = 0; bj < 2; ++bj) {
;                         const int c0 = c00 + bj * 128;
;                         float* xn = xdst + (size_t)r * DM + c0;
;                         const f32x4 y0 = xv[m2][bj][0] + gt[bj][0] * acc[ai][bj][m][0], y1 = xv[m2][bj][1] + gt[bj][1] * acc[ai][bj][m][1];
;                         *(f32x4*)xn = y0; *(f32x4*)(xn + 4) = y1;
;                         if (Hn) {
;                             ss += y0[0] * y0[0] + y0[1] * y0[1] + y0[2] * y0[2] + y0[3] * y0[3] + y1[0] * y1[0] + y1[1] * y1[1] + y1[2] * y1[2] + y1[3] * y1[3];
;                             const f32x4 h0 = y0 * gh[bj][0], h1 = y1 * gh[bj][1];
;                             u32x4 w; w.x = cvtpk(h0[0], h0[1]); w.y = cvtpk(h0[2], h0[3]); w.z = cvtpk(h1[0], h1[1]); w.w = cvtpk(h1[2], h1[3]);
;                             *(u32x4*)(Hn + (size_t)r * DM + c0) = w;
;                         }
;                     }
;                     if (Hn) {
;                         ss += __shfl_xor(ss, 16); ss += __shfl_xor(ss, 32);
;                         if (fq == 0) atomicAdd(rsn + r, ss);
;                     }
.LBB0_1893:
	v_ashrrev_i32_e32 v131, 31, v130
	v_lshlrev_b64 v[22:23], 12, v[130:131]
	v_or_b32_e32 v132, 16, v130
	v_lshl_add_u64 v[22:23], s[92:93], 0, v[22:23]
	v_ashrrev_i32_e32 v133, 31, v132
	v_lshl_add_u64 v[136:137], v[22:23], 0, v[236:237]
	v_lshlrev_b64 v[22:23], 12, v[132:133]
	v_lshl_add_u64 v[22:23], s[92:93], 0, v[22:23]
	v_lshl_add_u64 v[134:135], v[22:23], 0, v[236:237]
	global_load_dwordx4 v[122:125], v[136:137], off offset:16
	global_load_dwordx4 v[126:129], v[136:137], off
	global_load_dwordx4 v[114:117], v[136:137], off offset:528
	global_load_dwordx4 v[118:121], v[136:137], off offset:512
	global_load_dwordx4 v[30:33], v[134:135], off offset:16
	global_load_dwordx4 v[34:37], v[134:135], off
	global_load_dwordx4 v[22:25], v[134:135], off offset:528
	global_load_dwordx4 v[26:29], v[134:135], off offset:512
	s_mov_b64 s[2:3], -1
	s_and_b64 vcc, exec, s[72:73]
	s_waitcnt vmcnt(7)
	v_pk_fma_f32 v[124:125], v[100:101], v[108:109], v[124:125]
	s_waitcnt vmcnt(6)
	v_pk_fma_f32 v[128:129], v[104:105], v[112:113], v[128:129]
	v_pk_fma_f32 v[126:127], v[102:103], v[110:111], v[126:127]
	v_pk_fma_f32 v[122:123], v[98:99], v[106:107], v[122:123]
	s_waitcnt vmcnt(4)
	v_pk_fma_f32 v[102:103], v[94:95], v[42:43], v[118:119]
	v_pk_fma_f32 v[98:99], v[90:91], v[38:39], v[114:115]
	global_store_dwordx4 v[136:137], v[126:129], off nt
	global_store_dwordx4 v[136:137], v[122:125], off offset:16 nt
	s_cbranch_vccz .LBB0_1895
	v_pk_fma_f32 v[104:105], v[96:97], v[44:45], v[120:121]
	v_pk_fma_f32 v[100:101], v[92:93], v[40:41], v[116:117]
	global_store_dwordx4 v[136:137], v[102:105], off offset:512 nt
	global_store_dwordx4 v[136:137], v[98:101], off offset:528 nt
	s_mov_b64 s[2:3], 0
.LBB0_1895:
	s_andn2_b64 vcc, exec, s[2:3]
	s_cbranch_vccnz .LBB0_1899
	v_mul_f32_e32 v118, v127, v127
	v_fmac_f32_e32 v118, v126, v126
	v_fmac_f32_e32 v118, v128, v128
	v_fmac_f32_e32 v118, v129, v129
	v_fmac_f32_e32 v118, v122, v122
	v_pk_mul_f32 v[90:91], v[8:9], v[128:129]
	v_fmac_f32_e32 v118, v123, v123
	v_pk_mul_f32 v[104:105], v[10:11], v[122:123]
	v_cvt_pk_bf16_f32 v123, v90, v91
	v_lshlrev_b64 v[90:91], 11, v[130:131]
	v_lshl_add_u64 v[90:91], s[80:81], 0, v[90:91]
	v_lshl_add_u64 v[114:115], v[234:235], 1, v[90:91]
	v_mul_f32_e32 v90, v103, v103
	v_fmac_f32_e32 v118, v124, v124
	v_pk_mul_f32 v[100:101], v[12:13], v[124:125]
	v_cvt_pk_bf16_f32 v124, v104, v105
	v_pk_fma_f32 v[104:105], v[96:97], v[44:45], v[120:121]
	v_fmac_f32_e32 v90, v102, v102
	v_fmac_f32_e32 v90, v104, v104
	v_fmac_f32_e32 v90, v105, v105
	v_fmac_f32_e32 v90, v98, v98
	v_fmac_f32_e32 v118, v125, v125
	v_cvt_pk_bf16_f32 v125, v100, v101
	v_pk_fma_f32 v[100:101], v[92:93], v[40:41], v[116:117]
	v_fmac_f32_e32 v90, v99, v99
	v_pk_mul_f32 v[94:95], v[6:7], v[126:127]
	v_fmac_f32_e32 v90, v100, v100
	v_cvt_pk_bf16_f32 v122, v94, v95
	v_fmac_f32_e32 v90, v101, v101
	v_and_b32_e32 v91, 64, v248
	global_store_dwordx4 v[114:115], v[122:125], off
	global_store_dwordx4 v[136:137], v[102:105], off offset:512 nt
	global_store_dwordx4 v[136:137], v[98:101], off offset:528 nt
	v_pk_mul_f32 v[94:95], v[16:17], v[104:105]
	v_add_f32_e32 v93, v118, v90
	v_xor_b32_e32 v90, 16, v248
	v_add_u32_e32 v104, 64, v91
	v_cmp_lt_i32_e32 vcc, v90, v104
	v_pk_mul_f32 v[96:97], v[20:21], v[100:101]
	v_pk_mul_f32 v[98:99], v[18:19], v[98:99]
	v_cndmask_b32_e32 v90, v248, v90, vcc
	v_lshlrev_b32_e32 v90, 2, v90
	ds_bpermute_b32 v105, v90, v93
	v_pk_mul_f32 v[90:91], v[14:15], v[102:103]
	s_nop 0
	v_cvt_pk_bf16_f32 v92, v90, v91
	v_xor_b32_e32 v91, 32, v248
	v_cmp_lt_i32_e32 vcc, v91, v104
	s_waitcnt lgkmcnt(0)
	v_add_f32_e32 v90, v93, v105
	v_cvt_pk_bf16_f32 v93, v94, v95
	v_cndmask_b32_e32 v91, v248, v91, vcc
	v_lshlrev_b32_e32 v91, 2, v91
	ds_bpermute_b32 v91, v91, v90
	v_cvt_pk_bf16_f32 v94, v98, v99
	v_cvt_pk_bf16_f32 v95, v96, v97
	global_store_dwordx4 v[114:115], v[92:95], off offset:256
	s_and_saveexec_b64 s[2:3], s[38:39]
	s_cbranch_execz .LBB0_1898
	v_readlane_b32 s28, v251, 45
	v_readlane_b32 s29, v251, 46
	s_waitcnt lgkmcnt(0)
	v_add_f32_e32 v90, v90, v91
	v_lshl_add_u64 v[92:93], v[130:131], 2, s[28:29]
	global_atomic_add_f32 v[92:93], v90, off

; __device__ __forceinline__ unsigned cvtpk(float lo, float hi) { f32x2_t v = {lo, hi}; bf16x2_t b = __builtin_convertvector(v, bf16x2_t); return __builtin_bit_cast(unsigned, b); }
;     __device__ __forceinline__ void operator()(const f32x4 (&acc)[2][2][4][2], const Unit& u, int wr, int wc, int fr, int fq) const {
;     ...
;                 for (int m2 = 0; m2 < 2; ++m2) {
;                     const int m = 2 * mp + m2;
;                     const int r = rbase + 16 * m;
;                     float ss = 0.f;
; #pragma unroll
;                     for (int bj = 0; bj < 2; ++bj) {
;                         const int c0 = c00 + bj * 128;
;                         float* xn = xdst + (size_t)r * DM + c0;
;                         const f32x4 y0 = xv[m2][bj][0] + gt[bj][0] * acc[ai][bj][m][0], y1 = xv[m2][bj][1] + gt[bj][1] * acc[ai][bj][m][1];
;                         *(f32x4*)xn = y0; *(f32x4*)(xn + 4) = y1;
;                         if (Hn) {
;                             ss += y0[0] * y0[0] + y0[1] * y0[1] + y0[2] * y0[2] + y0[3] * y0[3] + y1[0] * y1[0] + y1[1] * y1[1] + y1[2] * y1[2] + y1[3] * y1[3];
;                             const f32x4 h0 = y0 * gh[bj][0], h1 = y1 * gh[bj][1];
;                             u32x4 w; w.x = cvtpk(h0[0], h0[1]); w.y = cvtpk(h0[2], h0[3]); w.z = cvtpk(h1[0], h1[1]); w.w = cvtpk(h1[2], h1[3]);
;                             *(u32x4*)(Hn + (size_t)r * DM + c0) = w;
;                         }
;                     }
;                     if (Hn) {
;                         ss += __shfl_xor(ss, 16); ss += __shfl_xor(ss, 32);
;                         if (fq == 0) atomicAdd(rsn + r, ss);
;                     }
.LBB0_1899:
	s_waitcnt vmcnt(4)
	v_pk_fma_f32 v[88:89], v[88:89], v[112:113], v[36:37]
	v_pk_fma_f32 v[86:87], v[86:87], v[110:111], v[34:35]
	v_pk_fma_f32 v[84:85], v[84:85], v[108:109], v[32:33]
	v_pk_fma_f32 v[82:83], v[82:83], v[106:107], v[30:31]
	s_mov_b64 s[2:3], -1
	s_and_b64 vcc, exec, s[72:73]
	s_waitcnt vmcnt(2)
	v_pk_fma_f32 v[34:35], v[78:79], v[42:43], v[26:27]
	v_pk_fma_f32 v[30:31], v[74:75], v[38:39], v[22:23]
	global_store_dwordx4 v[134:135], v[86:89], off nt
	global_store_dwordx4 v[134:135], v[82:85], off offset:16 nt
	s_cbranch_vccz .LBB0_1901
	v_pk_fma_f32 v[36:37], v[80:81], v[44:45], v[28:29]
	v_pk_fma_f32 v[32:33], v[76:77], v[40:41], v[24:25]
	global_store_dwordx4 v[134:135], v[34:37], off offset:512 nt
	global_store_dwordx4 v[134:135], v[30:33], off offset:528 nt
	s_mov_b64 s[2:3], 0
.LBB0_1901:
	s_andn2_b64 vcc, exec, s[2:3]
	s_cbranch_vccnz .LBB0_1905
	v_mul_f32_e32 v78, v87, v87
	v_fmac_f32_e32 v78, v86, v86
	v_fmac_f32_e32 v78, v88, v88
	v_fmac_f32_e32 v78, v89, v89
	v_fmac_f32_e32 v78, v82, v82
	v_pk_mul_f32 v[22:23], v[8:9], v[88:89]
	v_fmac_f32_e32 v78, v83, v83
	v_pk_mul_f32 v[36:37], v[10:11], v[82:83]
	v_cvt_pk_bf16_f32 v83, v22, v23
	v_lshlrev_b64 v[22:23], 11, v[132:133]
	v_lshl_add_u64 v[22:23], s[80:81], 0, v[22:23]
	v_lshl_add_u64 v[74:75], v[234:235], 1, v[22:23]
	v_mul_f32_e32 v22, v35, v35
	v_fmac_f32_e32 v78, v84, v84
	v_pk_mul_f32 v[32:33], v[12:13], v[84:85]
	v_cvt_pk_bf16_f32 v84, v36, v37
	v_pk_fma_f32 v[36:37], v[80:81], v[44:45], v[28:29]
	v_fmac_f32_e32 v22, v34, v34
	v_fmac_f32_e32 v22, v36, v36
	v_fmac_f32_e32 v22, v37, v37
	v_fmac_f32_e32 v22, v30, v30
	v_fmac_f32_e32 v78, v85, v85
	v_cvt_pk_bf16_f32 v85, v32, v33
	v_pk_fma_f32 v[32:33], v[76:77], v[40:41], v[24:25]
	v_fmac_f32_e32 v22, v31, v31
	v_pk_mul_f32 v[26:27], v[6:7], v[86:87]
	v_fmac_f32_e32 v22, v32, v32
	v_cvt_pk_bf16_f32 v82, v26, v27
	v_fmac_f32_e32 v22, v33, v33
	v_and_b32_e32 v23, 64, v248
	global_store_dwordx4 v[74:75], v[82:85], off
	global_store_dwordx4 v[134:135], v[34:37], off offset:512 nt
	global_store_dwordx4 v[134:135], v[30:33], off offset:528 nt
	v_pk_mul_f32 v[26:27], v[16:17], v[36:37]
	v_add_f32_e32 v25, v78, v22
	v_xor_b32_e32 v22, 16, v248
	v_add_u32_e32 v36, 64, v23
	v_cmp_lt_i32_e32 vcc, v22, v36
	v_pk_mul_f32 v[28:29], v[20:21], v[32:33]
	v_pk_mul_f32 v[30:31], v[18:19], v[30:31]
	v_cndmask_b32_e32 v22, v248, v22, vcc
	v_lshlrev_b32_e32 v22, 2, v22
	ds_bpermute_b32 v37, v22, v25
	v_pk_mul_f32 v[22:23], v[14:15], v[34:35]
	s_nop 0
	v_cvt_pk_bf16_f32 v24, v22, v23
	v_xor_b32_e32 v23, 32, v248
	v_cmp_lt_i32_e32 vcc, v23, v36
	s_waitcnt lgkmcnt(0)
	v_add_f32_e32 v22, v25, v37
	v_cvt_pk_bf16_f32 v25, v26, v27
	v_cndmask_b32_e32 v23, v248, v23, vcc
	v_lshlrev_b32_e32 v23, 2, v23
	ds_bpermute_b32 v23, v23, v22
	v_cvt_pk_bf16_f32 v26, v30, v31
	v_cvt_pk_bf16_f32 v27, v28, v29
	global_store_dwordx4 v[74:75], v[24:27], off offset:256
	s_and_saveexec_b64 s[2:3], s[38:39]
	s_cbranch_execz .LBB0_1904
	v_readlane_b32 s28, v251, 45
	v_readlane_b32 s29, v251, 46
	s_waitcnt lgkmcnt(0)
	v_add_f32_e32 v22, v22, v23
	v_lshl_add_u64 v[24:25], v[132:133], 2, s[28:29]
	global_atomic_add_f32 v[24:25], v22, off

; __device__ __forceinline__ unsigned cvtpk(float lo, float hi) { f32x2_t v = {lo, hi}; bf16x2_t b = __builtin_convertvector(v, bf16x2_t); return __builtin_bit_cast(unsigned, b); }
;     __device__ __forceinline__ void operator()(const f32x4 (&acc)[2][2][4][2], const Unit& u, int wr, int wc, int fr, int fq) const {
;     ...
;                 for (int m2 = 0; m2 < 2; ++m2) {
;                     const int r = rbase + 16 * (2 * mp + m2);
;                     const float* xo = from_input ? ((r < MP) ? xp + (size_t)r * DM : xs + (size_t)(r - MP) * DM) : xbuf + (size_t)r * DM;
; #pragma unroll
;                     for (int bj = 0; bj < 2; ++bj) { xv[m2][bj][0] = *(const f32x4*)(xo + c00 + bj * 128); xv[m2][bj][1] = *(const f32x4*)(xo + c00 + bj * 128 + 4); }
;                 }
; #pragma unroll
;                 for (int m2 = 0; m2 < 2; ++m2) {
;                     const int m = 2 * mp + m2;
;                     const int r = rbase + 16 * m;
;                     float ss = 0.f;
; #pragma unroll
;                     for (int bj = 0; bj < 2; ++bj) {
;                         const int c0 = c00 + bj * 128;
;                         float* xn = xdst + (size_t)r * DM + c0;
;                         const f32x4 y0 = xv[m2][bj][0] + gt[bj][0] * acc[ai][bj][m][0], y1 = xv[m2][bj][1] + gt[bj][1] * acc[ai][bj][m][1];
;                         *(f32x4*)xn = y0; *(f32x4*)(xn + 4) = y1;
;                         if (Hn) {
;                             ss += y0[0] * y0[0] + y0[1] * y0[1] + y0[2] * y0[2] + y0[3] * y0[3] + y1[0] * y1[0] + y1[1] * y1[1] + y1[2] * y1[2] + y1[3] * y1[3];
;                             const f32x4 h0 = y0 * gh[bj][0], h1 = y1 * gh[bj][1];
;                             u32x4 w; w.x = cvtpk(h0[0], h0[1]); w.y = cvtpk(h0[2], h0[3]); w.z = cvtpk(h1[0], h1[1]); w.w = cvtpk(h1[2], h1[3]);
;                             *(u32x4*)(Hn + (size_t)r * DM + c0) = w;
;                         }
;                     }
;                     if (Hn) {
;                         ss += __shfl_xor(ss, 16); ss += __shfl_xor(ss, 32);
;                         if (fq == 0) atomicAdd(rsn + r, ss);
;                     }
.LBB0_1905:
	v_or_b32_e32 v94, 32, v130
	v_ashrrev_i32_e32 v95, 31, v94
	s_waitcnt lgkmcnt(0)
	v_lshlrev_b64 v[22:23], 12, v[94:95]
	v_or_b32_e32 v90, 48, v130
	v_lshl_add_u64 v[22:23], s[92:93], 0, v[22:23]
	v_ashrrev_i32_e32 v91, 31, v90
	v_lshl_add_u64 v[96:97], v[22:23], 0, v[236:237]
	v_lshlrev_b64 v[22:23], 12, v[90:91]
	v_lshl_add_u64 v[22:23], s[92:93], 0, v[22:23]
	v_lshl_add_u64 v[92:93], v[22:23], 0, v[236:237]
	global_load_dwordx4 v[82:85], v[96:97], off offset:16
	global_load_dwordx4 v[86:89], v[96:97], off
	global_load_dwordx4 v[74:77], v[96:97], off offset:528
	global_load_dwordx4 v[78:81], v[96:97], off offset:512
	global_load_dwordx4 v[30:33], v[92:93], off offset:16
	global_load_dwordx4 v[34:37], v[92:93], off
	global_load_dwordx4 v[22:25], v[92:93], off offset:528
	global_load_dwordx4 v[26:29], v[92:93], off offset:512
	s_mov_b64 s[2:3], -1
	s_and_b64 vcc, exec, s[72:73]
	s_waitcnt vmcnt(7)
	v_pk_fma_f32 v[84:85], v[68:69], v[108:109], v[84:85]
	s_waitcnt vmcnt(6)
	v_pk_fma_f32 v[88:89], v[72:73], v[112:113], v[88:89]
	v_pk_fma_f32 v[86:87], v[70:71], v[110:111], v[86:87]
	v_pk_fma_f32 v[82:83], v[66:67], v[106:107], v[82:83]
	s_waitcnt vmcnt(4)
	v_pk_fma_f32 v[70:71], v[62:63], v[42:43], v[78:79]
	v_pk_fma_f32 v[66:67], v[58:59], v[38:39], v[74:75]
	global_store_dwordx4 v[96:97], v[86:89], off nt
	global_store_dwordx4 v[96:97], v[82:85], off offset:16 nt
	s_cbranch_vccz .LBB0_1907
	v_pk_fma_f32 v[72:73], v[64:65], v[44:45], v[80:81]
	v_pk_fma_f32 v[68:69], v[60:61], v[40:41], v[76:77]
	global_store_dwordx4 v[96:97], v[70:73], off offset:512 nt
	global_store_dwordx4 v[96:97], v[66:69], off offset:528 nt
	s_mov_b64 s[2:3], 0
.LBB0_1907:
	s_andn2_b64 vcc, exec, s[2:3]
	s_cbranch_vccnz .LBB0_1911
	v_pk_mul_f32 v[58:59], v[8:9], v[88:89]
	v_pk_mul_f32 v[62:63], v[6:7], v[86:87]
	v_cvt_pk_bf16_f32 v73, v58, v59
	v_lshlrev_b64 v[58:59], 11, v[94:95]
	v_pk_mul_f32 v[68:69], v[12:13], v[84:85]
	v_pk_mul_f32 v[74:75], v[10:11], v[82:83]
	v_lshl_add_u64 v[58:59], s[80:81], 0, v[58:59]
	v_mul_f32_e32 v98, v87, v87
	v_cvt_pk_bf16_f32 v72, v62, v63
	v_cvt_pk_bf16_f32 v74, v74, v75
	v_cvt_pk_bf16_f32 v75, v68, v69
	v_lshl_add_u64 v[78:79], v[234:235], 1, v[58:59]
	v_mul_f32_e32 v58, v71, v71
	v_fmac_f32_e32 v98, v86, v86
	global_store_dwordx4 v[78:79], v[72:75], off
	v_fmac_f32_e32 v58, v70, v70
	v_fmac_f32_e32 v98, v88, v88
	v_pk_fma_f32 v[72:73], v[64:65], v[44:45], v[80:81]
	v_fmac_f32_e32 v98, v89, v89
	v_fmac_f32_e32 v58, v72, v72
	v_fmac_f32_e32 v58, v73, v73
	v_fmac_f32_e32 v98, v82, v82
	v_fmac_f32_e32 v58, v66, v66
	v_fmac_f32_e32 v98, v83, v83
	v_pk_fma_f32 v[68:69], v[60:61], v[40:41], v[76:77]
	v_fmac_f32_e32 v58, v67, v67
	v_fmac_f32_e32 v98, v84, v84
	v_fmac_f32_e32 v58, v68, v68
	v_fmac_f32_e32 v98, v85, v85
	v_fmac_f32_e32 v58, v69, v69
	v_and_b32_e32 v59, 64, v248
	global_store_dwordx4 v[96:97], v[70:73], off offset:512 nt
	global_store_dwordx4 v[96:97], v[66:69], off offset:528 nt
	v_pk_mul_f32 v[62:63], v[16:17], v[72:73]
	v_add_f32_e32 v61, v98, v58
	v_xor_b32_e32 v58, 16, v248
	v_add_u32_e32 v72, 64, v59
	v_cmp_lt_i32_e32 vcc, v58, v72
	v_pk_mul_f32 v[64:65], v[20:21], v[68:69]
	v_pk_mul_f32 v[66:67], v[18:19], v[66:67]
	v_cndmask_b32_e32 v58, v248, v58, vcc
	v_lshlrev_b32_e32 v58, 2, v58
	ds_bpermute_b32 v73, v58, v61
	v_pk_mul_f32 v[58:59], v[14:15], v[70:71]
	s_nop 0
	v_cvt_pk_bf16_f32 v60, v58, v59
	v_xor_b32_e32 v59, 32, v248
	v_cmp_lt_i32_e32 vcc, v59, v72
	s_waitcnt lgkmcnt(0)
	v_add_f32_e32 v58, v61, v73
	v_cvt_pk_bf16_f32 v61, v62, v63
	v_cndmask_b32_e32 v59, v248, v59, vcc
	v_lshlrev_b32_e32 v59, 2, v59
	ds_bpermute_b32 v59, v59, v58
	v_cvt_pk_bf16_f32 v62, v66, v67
	v_cvt_pk_bf16_f32 v63, v64, v65
	global_store_dwordx4 v[78:79], v[60:63], off offset:256
	s_and_saveexec_b64 s[2:3], s[38:39]
	s_cbranch_execz .LBB0_1910
	v_readlane_b32 s28, v251, 45
	v_readlane_b32 s29, v251, 46
	s_waitcnt lgkmcnt(0)
	v_add_f32_e32 v58, v58, v59
	v_lshl_add_u64 v[60:61], v[94:95], 2, s[28:29]
	global_atomic_add_f32 v[60:61], v58, off

; __device__ __forceinline__ unsigned cvtpk(float lo, float hi) { f32x2_t v = {lo, hi}; bf16x2_t b = __builtin_convertvector(v, bf16x2_t); return __builtin_bit_cast(unsigned, b); }
;     __device__ __forceinline__ void operator()(const f32x4 (&acc)[2][2][4][2], const Unit& u, int wr, int wc, int fr, int fq) const {
;     ...
;                 for (int m2 = 0; m2 < 2; ++m2) {
;                     const int m = 2 * mp + m2;
;                     const int r = rbase + 16 * m;
;                     float ss = 0.f;
; #pragma unroll
;                     for (int bj = 0; bj < 2; ++bj) {
;                         const int c0 = c00 + bj * 128;
;                         float* xn = xdst + (size_t)r * DM + c0;
;                         const f32x4 y0 = xv[m2][bj][0] + gt[bj][0] * acc[ai][bj][m][0], y1 = xv[m2][bj][1] + gt[bj][1] * acc[ai][bj][m][1];
;                         *(f32x4*)xn = y0; *(f32x4*)(xn + 4) = y1;
;                         if (Hn) {
;                             ss += y0[0] * y0[0] + y0[1] * y0[1] + y0[2] * y0[2] + y0[3] * y0[3] + y1[0] * y1[0] + y1[1] * y1[1] + y1[2] * y1[2] + y1[3] * y1[3];
;                             const f32x4 h0 = y0 * gh[bj][0], h1 = y1 * gh[bj][1];
;                             u32x4 w; w.x = cvtpk(h0[0], h0[1]); w.y = cvtpk(h0[2], h0[3]); w.z = cvtpk(h1[0], h1[1]); w.w = cvtpk(h1[2], h1[3]);
;                             *(u32x4*)(Hn + (size_t)r * DM + c0) = w;
;                         }
;                     }
;                     if (Hn) {
;                         ss += __shfl_xor(ss, 16); ss += __shfl_xor(ss, 32);
;                         if (fq == 0) atomicAdd(rsn + r, ss);
;                     }
.LBB0_1911:
	s_waitcnt vmcnt(4)
	v_pk_fma_f32 v[56:57], v[56:57], v[112:113], v[36:37]
	v_pk_fma_f32 v[54:55], v[54:55], v[110:111], v[34:35]
	v_pk_fma_f32 v[52:53], v[52:53], v[108:109], v[32:33]
	v_pk_fma_f32 v[50:51], v[50:51], v[106:107], v[30:31]
	s_mov_b64 s[2:3], -1
	s_and_b64 vcc, exec, s[72:73]
	s_waitcnt vmcnt(2)
	v_pk_fma_f32 v[34:35], v[46:47], v[42:43], v[26:27]
	v_pk_fma_f32 v[30:31], v[0:1], v[38:39], v[22:23]
	global_store_dwordx4 v[92:93], v[54:57], off nt
	global_store_dwordx4 v[92:93], v[50:53], off offset:16 nt
	s_cbranch_vccz .LBB0_1913
	v_pk_fma_f32 v[36:37], v[48:49], v[44:45], v[28:29]
	v_pk_fma_f32 v[32:33], v[2:3], v[40:41], v[24:25]
	global_store_dwordx4 v[92:93], v[34:37], off offset:512 nt
	global_store_dwordx4 v[92:93], v[30:33], off offset:528 nt
	s_mov_b64 s[2:3], 0
.LBB0_1913:
	s_andn2_b64 vcc, exec, s[2:3]
	s_cbranch_vccnz .LBB0_1917
	v_pk_mul_f32 v[0:1], v[8:9], v[56:57]
	v_pk_mul_f32 v[6:7], v[6:7], v[54:55]
	v_mul_f32_e32 v22, v55, v55
	v_cvt_pk_bf16_f32 v6, v6, v7
	v_cvt_pk_bf16_f32 v7, v0, v1
	v_lshlrev_b64 v[0:1], 11, v[90:91]
	v_lshl_add_u64 v[0:1], s[80:81], 0, v[0:1]
	v_pk_mul_f32 v[8:9], v[10:11], v[50:51]
	v_lshl_add_u64 v[10:11], v[234:235], 1, v[0:1]
	v_mul_f32_e32 v0, v35, v35
	v_fmac_f32_e32 v22, v54, v54
	v_pk_fma_f32 v[36:37], v[48:49], v[44:45], v[28:29]
	v_fmac_f32_e32 v0, v34, v34
	v_fmac_f32_e32 v22, v56, v56
	v_fmac_f32_e32 v0, v36, v36
	v_fmac_f32_e32 v22, v57, v57
	v_fmac_f32_e32 v0, v37, v37
	v_fmac_f32_e32 v22, v50, v50
	v_fmac_f32_e32 v0, v30, v30
	v_fmac_f32_e32 v22, v51, v51
	v_pk_fma_f32 v[32:33], v[2:3], v[40:41], v[24:25]
	v_fmac_f32_e32 v0, v31, v31
	v_fmac_f32_e32 v22, v52, v52
	v_pk_mul_f32 v[12:13], v[12:13], v[52:53]
	v_fmac_f32_e32 v0, v32, v32
	v_fmac_f32_e32 v22, v53, v53
	v_cvt_pk_bf16_f32 v8, v8, v9
	v_cvt_pk_bf16_f32 v9, v12, v13
	v_fmac_f32_e32 v0, v33, v33
	v_and_b32_e32 v1, 64, v248
	global_store_dwordx4 v[10:11], v[6:9], off
	v_pk_mul_f32 v[2:3], v[16:17], v[36:37]
	v_add_u32_e32 v16, 64, v1
	v_add_f32_e32 v7, v22, v0
	v_xor_b32_e32 v0, 16, v248
	v_cmp_lt_i32_e32 vcc, v0, v16
	v_pk_mul_f32 v[12:13], v[20:21], v[32:33]
	v_pk_mul_f32 v[8:9], v[18:19], v[30:31]
	v_cndmask_b32_e32 v0, v248, v0, vcc
	v_lshlrev_b32_e32 v0, 2, v0
	ds_bpermute_b32 v17, v0, v7
	v_pk_mul_f32 v[0:1], v[14:15], v[34:35]
	v_cvt_pk_bf16_f32 v8, v8, v9
	v_cvt_pk_bf16_f32 v6, v0, v1
	v_xor_b32_e32 v1, 32, v248
	v_cmp_lt_i32_e32 vcc, v1, v16
	s_waitcnt lgkmcnt(0)
	v_add_f32_e32 v0, v7, v17
	v_cvt_pk_bf16_f32 v7, v2, v3
	v_cndmask_b32_e32 v1, v248, v1, vcc
	v_lshlrev_b32_e32 v1, 2, v1
	ds_bpermute_b32 v1, v1, v0
	v_cvt_pk_bf16_f32 v9, v12, v13
	global_store_dwordx4 v[92:93], v[34:37], off offset:512 nt
	global_store_dwordx4 v[92:93], v[30:33], off offset:528 nt
	global_store_dwordx4 v[10:11], v[6:9], off offset:256
	s_and_saveexec_b64 s[2:3], s[38:39]
	s_cbranch_execz .LBB0_1916
	v_readlane_b32 s28, v251, 45
	v_readlane_b32 s29, v251, 46
	s_waitcnt lgkmcnt(0)
	v_add_f32_e32 v0, v0, v1
	v_lshl_add_u64 v[2:3], v[90:91], 2, s[28:29]
	global_atomic_add_f32 v[2:3], v0, off
